# GEMM K-loops: in the two read-free segments the M0 write is issued before the two SALU address adds so the first LDS-DMA piece needs no s_nop
# baseline (speedup 1.0000x reference)
; #define PG8_STAGE(bufoff, gbase, voff) do { _Pragma("unroll") for (int _i = 0; _i < 2; ++_i) \
;         __builtin_amdgcn_global_load_lds((const unsigned*)((const char*)(gbase) + (voff)[_i]), (PG8_LAS unsigned*)(lds + (bufoff) + ldsw + _i * 8192), 16, 0, 0); } while (0)
; #define PG8_LDA(dst, b, h) do { _Pragma("unroll") for (int m = 0; m < 4; ++m) _Pragma("unroll") for (int k = 0; k < 2; ++k) dst[m][k] = *(const PG8_LAS bf16x8*)(lds + PG8_SA(b, h) + aoff + m * 2048 + k * 1024); } while (0)
; #define PG8_LDB(dst, b, h) do { _Pragma("unroll") for (int n = 0; n < 2; ++n) _Pragma("unroll") for (int k = 0; k < 2; ++k) dst[n][k] = *(const PG8_LAS bf16x8*)(lds + PG8_SB(b, h) + boff + n * 2048 + k * 1024); } while (0)
; #define PG8_MMA(ai, bj, At, Bt) do { __builtin_amdgcn_s_setprio(1); _Pragma("unroll") for (int m = 0; m < 4; ++m) _Pragma("unroll") for (int n = 0; n < 2; ++n) _Pragma("unroll") for (int k = 0; k < 2; ++k) \
;         acc[ai][bj][m][n] = __builtin_amdgcn_mfma_f32_16x16x32_bf16(Bt[n][k], At[m][k], acc[ai][bj][m][n], 0, 0, 0); __builtin_amdgcn_s_setprio(0); } while (0)
; #define PG8_WAIT_V(n) asm volatile("s_waitcnt vmcnt(" #n ")" ::: "memory")
; template <class Epi, class Sched>
; __device__ __forceinline__ void gemm_phase(PG8_LAS unsigned char* lds, const Gemm g, const Sched& S, const Epi& E) {
;     ...
;         for (int t = 0; t < nt; t += 2) {
;             const bool last = (t == nt - 2);
;             const char* a1 = cA + (size_t)(t + 1) * kstep;
;             const char* a2 = last ? nA : cA + (size_t)(t + 2) * kstep; const char* b2 = last ? nB : cB + (size_t)(t + 2) * kstep;
;             const char* a3 = a2 + kstep; const char* b3 = b2 + kstep;
;             if (last && has_next) S.a_ready(nxt);
;             PG8_LDB(B0, 0, 0); PG8_SCHED; PG8_LDA(At, 0, 0); PG8_STAGE(PG8_SA(1, 1), a1 + hstep, voffA);
;             PG8_WAIT_L(8); PG8_BAR; PG8_WAIT_L(0); PG8_MMA(0, 0, At, B0); PG8_BAR; PG8_SCHED;
;             PG8_LDB(B1, 0, 1); PG8_STAGE(PG8_SB(0, 0), b2, voffB);
;             PG8_BAR; PG8_WAIT_L(0); PG8_MMA(0, 1, At, B1); PG8_BAR;
;             PG8_LDA(At, 0, 1); PG8_STAGE(PG8_SA(0, 0), a2, voffA);
;             PG8_BAR; PG8_WAIT_L(0); PG8_MMA(1, 0, At, B0); PG8_BAR; PG8_SCHED;
;             PG8_STAGE(PG8_SB(0, 1), b2 + hstep, voffB);
;             PG8_WAIT_V(6); PG8_BAR; PG8_MMA(1, 1, At, B1); PG8_BAR;
.LBB0_96:
	s_add_u32 s10, s8, 0x100
	s_addc_u32 s11, s9, 0
	v_add_u32_e32 v154, 0x10000, v139
	ds_read_b128 v[142:145], v154
	ds_read_b128 v[146:149], v154 offset:1024
	ds_read_b128 v[150:153], v154 offset:2048
	ds_read_b128 v[154:157], v154 offset:3072
	s_cmp_eq_u32 s45, 40
	s_cselect_b32 s15, s1, s11
	s_cselect_b32 s14, s0, s10
	s_cselect_b32 s13, s5, s44
	s_cselect_b32 s12, s4, s43
	s_add_i32 m0, s20, 0xc000
	ds_read_b128 v[158:161], v141
	ds_read_b128 v[162:165], v141 offset:1024
	ds_read_b128 v[166:169], v141 offset:2048
	ds_read_b128 v[170:173], v141 offset:3072
	ds_read_b128 v[178:181], v141 offset:4096
	ds_read_b128 v[182:185], v141 offset:5120
	ds_read_b128 v[186:189], v141 offset:6144
	global_load_lds_dwordx4 v134, s[8:9]
	s_add_i32 m0, s20, 0xe000
	ds_read_b128 v[190:193], v141 offset:7168
	global_load_lds_dwordx4 v136, s[8:9]
	s_waitcnt lgkmcnt(8)
	s_barrier
	s_waitcnt lgkmcnt(0)
	v_mfma_f32_16x16x32_bf16 v[124:127], v[142:145], v[158:161], v[124:127]
	v_mfma_f32_16x16x32_bf16 v[120:123], v[150:153], v[158:161], v[120:123]
	v_mfma_f32_16x16x32_bf16 v[116:119], v[142:145], v[166:169], v[116:119]
	v_mfma_f32_16x16x32_bf16 v[112:115], v[150:153], v[166:169], v[112:115]
	v_mfma_f32_16x16x32_bf16 v[100:103], v[142:145], v[178:181], v[100:103]
	v_mfma_f32_16x16x32_bf16 v[96:99], v[150:153], v[178:181], v[96:99]
	v_mfma_f32_16x16x32_bf16 v[84:87], v[142:145], v[186:189], v[84:87]
	v_mfma_f32_16x16x32_bf16 v[80:83], v[150:153], v[186:189], v[80:83]
	v_mfma_f32_16x16x32_bf16 v[124:127], v[146:149], v[162:165], v[124:127]
	v_mfma_f32_16x16x32_bf16 v[120:123], v[154:157], v[162:165], v[120:123]
	v_mfma_f32_16x16x32_bf16 v[116:119], v[146:149], v[170:173], v[116:119]
	v_mfma_f32_16x16x32_bf16 v[112:115], v[154:157], v[170:173], v[112:115]
	v_mfma_f32_16x16x32_bf16 v[100:103], v[146:149], v[182:185], v[100:103]
	v_mfma_f32_16x16x32_bf16 v[96:99], v[154:157], v[182:185], v[96:99]
	v_mfma_f32_16x16x32_bf16 v[84:87], v[146:149], v[190:193], v[84:87]
	v_mfma_f32_16x16x32_bf16 v[80:83], v[154:157], v[190:193], v[80:83]
	s_barrier
	s_add_i32 s47, 0, 0x14000
	v_add_u32_e32 v174, 0x14000, v139
	ds_read_b128 v[194:197], v174
	ds_read_b128 v[198:201], v174 offset:1024
	s_add_u32 s98, s12, 0x80
	s_addc_u32 s99, s13, 0
	s_add_i32 m0, s18, 0x10000
	ds_read_b128 v[202:205], v174 offset:2048
	global_load_lds_dwordx4 v176, s[12:13]
	s_add_i32 m0, s18, 0x12000
	ds_read_b128 v[206:209], v174 offset:3072
	global_load_lds_dwordx4 v128, s[12:13]
	s_barrier
	s_waitcnt lgkmcnt(0)
	v_mfma_f32_16x16x32_bf16 v[108:111], v[194:197], v[158:161], v[108:111]
	v_mfma_f32_16x16x32_bf16 v[104:107], v[202:205], v[158:161], v[104:107]
	v_mfma_f32_16x16x32_bf16 v[92:95], v[194:197], v[166:169], v[92:95]
	v_mfma_f32_16x16x32_bf16 v[88:91], v[202:205], v[166:169], v[88:91]
	v_mfma_f32_16x16x32_bf16 v[76:79], v[194:197], v[178:181], v[76:79]
	v_mfma_f32_16x16x32_bf16 v[72:75], v[202:205], v[178:181], v[72:75]
	v_mfma_f32_16x16x32_bf16 v[68:71], v[194:197], v[186:189], v[68:71]
	v_mfma_f32_16x16x32_bf16 v[64:67], v[202:205], v[186:189], v[64:67]
	v_mfma_f32_16x16x32_bf16 v[108:111], v[198:201], v[162:165], v[108:111]
	v_mfma_f32_16x16x32_bf16 v[104:107], v[206:209], v[162:165], v[104:107]
	v_mfma_f32_16x16x32_bf16 v[92:95], v[198:201], v[170:173], v[92:95]
	v_mfma_f32_16x16x32_bf16 v[88:91], v[206:209], v[170:173], v[88:91]
	v_mfma_f32_16x16x32_bf16 v[76:79], v[198:201], v[182:185], v[76:79]
	v_mfma_f32_16x16x32_bf16 v[72:75], v[206:209], v[182:185], v[72:75]
	v_mfma_f32_16x16x32_bf16 v[68:71], v[198:201], v[190:193], v[68:71]
	v_mfma_f32_16x16x32_bf16 v[64:67], v[206:209], v[190:193], v[64:67]
	s_mov_b32 m0, s20
	s_add_u32 s100, s14, 0x80
	s_addc_u32 s101, s15, 0
	s_barrier
	ds_read_b128 v[158:161], v141 offset:16384
	ds_read_b128 v[162:165], v141 offset:17408
	ds_read_b128 v[166:169], v141 offset:18432
	ds_read_b128 v[170:173], v141 offset:19456
	ds_read_b128 v[178:181], v141 offset:20480
	ds_read_b128 v[182:185], v141 offset:21504
	ds_read_b128 v[186:189], v141 offset:22528
	global_load_lds_dwordx4 v132, s[14:15]
	s_mov_b32 m0, s21
	ds_read_b128 v[190:193], v141 offset:23552
	global_load_lds_dwordx4 v130, s[14:15]
	s_barrier
	s_waitcnt lgkmcnt(0)
	v_mfma_f32_16x16x32_bf16 v[60:63], v[142:145], v[158:161], v[60:63]
	v_mfma_f32_16x16x32_bf16 v[56:59], v[150:153], v[158:161], v[56:59]
	v_mfma_f32_16x16x32_bf16 v[52:55], v[142:145], v[166:169], v[52:55]
	v_mfma_f32_16x16x32_bf16 v[48:51], v[150:153], v[166:169], v[48:51]
	v_mfma_f32_16x16x32_bf16 v[36:39], v[142:145], v[178:181], v[36:39]
	v_mfma_f32_16x16x32_bf16 v[32:35], v[150:153], v[178:181], v[32:35]
	v_mfma_f32_16x16x32_bf16 v[20:23], v[142:145], v[186:189], v[20:23]
	v_mfma_f32_16x16x32_bf16 v[16:19], v[150:153], v[186:189], v[16:19]
	v_mfma_f32_16x16x32_bf16 v[60:63], v[146:149], v[162:165], v[60:63]
	v_mfma_f32_16x16x32_bf16 v[56:59], v[154:157], v[162:165], v[56:59]
	v_mfma_f32_16x16x32_bf16 v[52:55], v[146:149], v[170:173], v[52:55]
	v_mfma_f32_16x16x32_bf16 v[48:51], v[154:157], v[170:173], v[48:51]
	v_mfma_f32_16x16x32_bf16 v[36:39], v[146:149], v[182:185], v[36:39]
	v_mfma_f32_16x16x32_bf16 v[32:35], v[154:157], v[182:185], v[32:35]
	v_mfma_f32_16x16x32_bf16 v[20:23], v[146:149], v[190:193], v[20:23]
	v_mfma_f32_16x16x32_bf16 v[16:19], v[154:157], v[190:193], v[16:19]
	s_barrier
	s_add_i32 m0, s18, 0x14000
	s_add_u32 s8, s12, 0xb0000
	s_addc_u32 s9, s13, 0
	global_load_lds_dwordx4 v176, s[8:9]
	s_add_i32 m0, s18, 0x16000
	s_nop 0
	global_load_lds_dwordx4 v128, s[8:9]
	s_waitcnt vmcnt(6)
	s_barrier
; #define PG8_STAGE(bufoff, gbase, voff) do { _Pragma("unroll") for (int _i = 0; _i < 2; ++_i) \
;         __builtin_amdgcn_global_load_lds((const unsigned*)((const char*)(gbase) + (voff)[_i]), (PG8_LAS unsigned*)(lds + (bufoff) + ldsw + _i * 8192), 16, 0, 0); } while (0)
; #define PG8_LDA(dst, b, h) do { _Pragma("unroll") for (int m = 0; m < 4; ++m) _Pragma("unroll") for (int k = 0; k < 2; ++k) dst[m][k] = *(const PG8_LAS bf16x8*)(lds + PG8_SA(b, h) + aoff + m * 2048 + k * 1024); } while (0)
; #define PG8_LDB(dst, b, h) do { _Pragma("unroll") for (int n = 0; n < 2; ++n) _Pragma("unroll") for (int k = 0; k < 2; ++k) dst[n][k] = *(const PG8_LAS bf16x8*)(lds + PG8_SB(b, h) + boff + n * 2048 + k * 1024); } while (0)
; #define PG8_MMA(ai, bj, At, Bt) do { __builtin_amdgcn_s_setprio(1); _Pragma("unroll") for (int m = 0; m < 4; ++m) _Pragma("unroll") for (int n = 0; n < 2; ++n) _Pragma("unroll") for (int k = 0; k < 2; ++k) \
;         acc[ai][bj][m][n] = __builtin_amdgcn_mfma_f32_16x16x32_bf16(Bt[n][k], At[m][k], acc[ai][bj][m][n], 0, 0, 0); __builtin_amdgcn_s_setprio(0); } while (0)
; #define PG8_WAIT_V(n) asm volatile("s_waitcnt vmcnt(" #n ")" ::: "memory")
; #define PG8_WAIT_L(n) asm volatile("s_waitcnt lgkmcnt(" #n ")" ::: "memory")
; #define PG8_BAR __builtin_amdgcn_s_barrier()
; #define PG8_SCHED __builtin_amdgcn_sched_barrier(0)
; template <class Epi, class Sched>
; __device__ __forceinline__ void gemm_phase(PG8_LAS unsigned char* lds, const Gemm g, const Sched& S, const Epi& E) {
;     ...
;             PG8_WAIT_V(6); PG8_BAR; PG8_MMA(1, 1, At, B1); PG8_BAR;
;             PG8_LDB(B0, 1, 0); PG8_SCHED; PG8_LDA(At, 1, 0); PG8_STAGE(PG8_SA(0, 1), a2 + hstep, voffA);
;             PG8_WAIT_L(8); PG8_BAR; PG8_WAIT_L(0); PG8_MMA(0, 0, At, B0); PG8_BAR; PG8_SCHED;
;             PG8_LDB(B1, 1, 1); PG8_STAGE(PG8_SB(1, 0), b3, voffB);
;             PG8_BAR; PG8_WAIT_L(0); PG8_MMA(0, 1, At, B1); PG8_BAR;
;             PG8_LDA(At, 1, 1); PG8_STAGE(PG8_SA(1, 0), a3, voffA);
;             PG8_BAR; PG8_WAIT_L(0); PG8_MMA(1, 0, At, B0); PG8_BAR; PG8_SCHED;
	v_mfma_f32_16x16x32_bf16 v[44:47], v[194:197], v[158:161], v[44:47]
	v_mfma_f32_16x16x32_bf16 v[40:43], v[202:205], v[158:161], v[40:43]
	v_mfma_f32_16x16x32_bf16 v[28:31], v[194:197], v[166:169], v[28:31]
	v_mfma_f32_16x16x32_bf16 v[24:27], v[202:205], v[166:169], v[24:27]
	v_mfma_f32_16x16x32_bf16 v[12:15], v[194:197], v[178:181], v[12:15]
	v_mfma_f32_16x16x32_bf16 v[8:11], v[202:205], v[178:181], v[8:11]
	v_mfma_f32_16x16x32_bf16 v[4:7], v[194:197], v[186:189], v[4:7]
	v_mfma_f32_16x16x32_bf16 v[0:3], v[202:205], v[186:189], v[0:3]
	v_mfma_f32_16x16x32_bf16 v[44:47], v[198:201], v[162:165], v[44:47]
	v_mfma_f32_16x16x32_bf16 v[40:43], v[206:209], v[162:165], v[40:43]
	v_mfma_f32_16x16x32_bf16 v[28:31], v[198:201], v[170:173], v[28:31]
	v_mfma_f32_16x16x32_bf16 v[24:27], v[206:209], v[170:173], v[24:27]
	v_mfma_f32_16x16x32_bf16 v[12:15], v[198:201], v[182:185], v[12:15]
	v_mfma_f32_16x16x32_bf16 v[8:11], v[206:209], v[182:185], v[8:11]
	v_mfma_f32_16x16x32_bf16 v[4:7], v[198:201], v[190:193], v[4:7]
	v_mfma_f32_16x16x32_bf16 v[0:3], v[206:209], v[190:193], v[0:3]
	s_add_i32 s46, 0, 0x18000
	v_add_u32_e32 v154, 0x18000, v139
	s_barrier
	ds_read_b128 v[142:145], v154
	ds_read_b128 v[146:149], v154 offset:1024
	ds_read_b128 v[150:153], v154 offset:2048
	ds_read_b128 v[154:157], v154 offset:3072
	s_add_u32 s8, s14, 0xb0000
	s_addc_u32 s9, s15, 0
	s_mov_b32 m0, s22
	ds_read_b128 v[158:161], v141 offset:32768
	ds_read_b128 v[162:165], v141 offset:33792
	ds_read_b128 v[166:169], v141 offset:34816
	ds_read_b128 v[170:173], v141 offset:35840
	ds_read_b128 v[178:181], v141 offset:36864
	ds_read_b128 v[182:185], v141 offset:37888
	ds_read_b128 v[186:189], v141 offset:38912
	global_load_lds_dwordx4 v132, s[8:9]
	s_mov_b32 m0, s23
	ds_read_b128 v[190:193], v141 offset:39936
	global_load_lds_dwordx4 v130, s[8:9]
	s_waitcnt lgkmcnt(8)
	s_barrier
	s_waitcnt lgkmcnt(0)
	v_mfma_f32_16x16x32_bf16 v[124:127], v[142:145], v[158:161], v[124:127]
	v_mfma_f32_16x16x32_bf16 v[120:123], v[150:153], v[158:161], v[120:123]
	v_mfma_f32_16x16x32_bf16 v[116:119], v[142:145], v[166:169], v[116:119]
	v_mfma_f32_16x16x32_bf16 v[112:115], v[150:153], v[166:169], v[112:115]
	v_mfma_f32_16x16x32_bf16 v[100:103], v[142:145], v[178:181], v[100:103]
	v_mfma_f32_16x16x32_bf16 v[96:99], v[150:153], v[178:181], v[96:99]
	v_mfma_f32_16x16x32_bf16 v[84:87], v[142:145], v[186:189], v[84:87]
	v_mfma_f32_16x16x32_bf16 v[80:83], v[150:153], v[186:189], v[80:83]
	v_mfma_f32_16x16x32_bf16 v[124:127], v[146:149], v[162:165], v[124:127]
	v_mfma_f32_16x16x32_bf16 v[120:123], v[154:157], v[162:165], v[120:123]
	v_mfma_f32_16x16x32_bf16 v[116:119], v[146:149], v[170:173], v[116:119]
	v_mfma_f32_16x16x32_bf16 v[112:115], v[154:157], v[170:173], v[112:115]
	v_mfma_f32_16x16x32_bf16 v[100:103], v[146:149], v[182:185], v[100:103]
	v_mfma_f32_16x16x32_bf16 v[96:99], v[154:157], v[182:185], v[96:99]
	v_mfma_f32_16x16x32_bf16 v[84:87], v[146:149], v[190:193], v[84:87]
	v_mfma_f32_16x16x32_bf16 v[80:83], v[154:157], v[190:193], v[80:83]
	s_barrier
	v_add_u32_e32 v206, 0x1c000, v139
	s_add_i32 m0, s18, 0x18000
	ds_read_b128 v[194:197], v206
	ds_read_b128 v[198:201], v206 offset:1024
	ds_read_b128 v[202:205], v206 offset:2048
	global_load_lds_dwordx4 v176, s[98:99]
	s_add_i32 m0, s18, 0x1a000
	ds_read_b128 v[206:209], v206 offset:3072
	global_load_lds_dwordx4 v128, s[98:99]
	s_barrier
	s_waitcnt lgkmcnt(0)
	v_mfma_f32_16x16x32_bf16 v[108:111], v[194:197], v[158:161], v[108:111]
	v_mfma_f32_16x16x32_bf16 v[104:107], v[202:205], v[158:161], v[104:107]
	v_mfma_f32_16x16x32_bf16 v[92:95], v[194:197], v[166:169], v[92:95]
	v_mfma_f32_16x16x32_bf16 v[88:91], v[202:205], v[166:169], v[88:91]
	v_mfma_f32_16x16x32_bf16 v[76:79], v[194:197], v[178:181], v[76:79]
	v_mfma_f32_16x16x32_bf16 v[72:75], v[202:205], v[178:181], v[72:75]
	v_mfma_f32_16x16x32_bf16 v[68:71], v[194:197], v[186:189], v[68:71]
	v_mfma_f32_16x16x32_bf16 v[64:67], v[202:205], v[186:189], v[64:67]
	v_mfma_f32_16x16x32_bf16 v[108:111], v[198:201], v[162:165], v[108:111]
	v_mfma_f32_16x16x32_bf16 v[104:107], v[206:209], v[162:165], v[104:107]
	v_mfma_f32_16x16x32_bf16 v[92:95], v[198:201], v[170:173], v[92:95]
	v_mfma_f32_16x16x32_bf16 v[88:91], v[206:209], v[170:173], v[88:91]
	v_mfma_f32_16x16x32_bf16 v[76:79], v[198:201], v[182:185], v[76:79]
	v_mfma_f32_16x16x32_bf16 v[72:75], v[206:209], v[182:185], v[72:75]
	v_mfma_f32_16x16x32_bf16 v[68:71], v[198:201], v[190:193], v[68:71]
	v_mfma_f32_16x16x32_bf16 v[64:67], v[206:209], v[190:193], v[64:67]
	s_mov_b32 m0, s27
	s_barrier
	ds_read_b128 v[158:161], v141 offset:49152
	ds_read_b128 v[162:165], v141 offset:50176
	ds_read_b128 v[166:169], v141 offset:51200
	ds_read_b128 v[170:173], v141 offset:52224
	ds_read_b128 v[178:181], v141 offset:53248
	ds_read_b128 v[182:185], v141 offset:54272
	ds_read_b128 v[186:189], v141 offset:55296
	global_load_lds_dwordx4 v132, s[100:101]
	s_mov_b32 m0, s28
	ds_read_b128 v[190:193], v141 offset:56320
	global_load_lds_dwordx4 v130, s[100:101]
	s_barrier
	s_waitcnt lgkmcnt(0)
	v_mfma_f32_16x16x32_bf16 v[60:63], v[142:145], v[158:161], v[60:63]
	v_mfma_f32_16x16x32_bf16 v[56:59], v[150:153], v[158:161], v[56:59]
	v_mfma_f32_16x16x32_bf16 v[52:55], v[142:145], v[166:169], v[52:55]
	v_mfma_f32_16x16x32_bf16 v[48:51], v[150:153], v[166:169], v[48:51]
	v_mfma_f32_16x16x32_bf16 v[36:39], v[142:145], v[178:181], v[36:39]
	v_mfma_f32_16x16x32_bf16 v[32:35], v[150:153], v[178:181], v[32:35]
	v_mfma_f32_16x16x32_bf16 v[20:23], v[142:145], v[186:189], v[20:23]
	v_mfma_f32_16x16x32_bf16 v[16:19], v[150:153], v[186:189], v[16:19]
	v_mfma_f32_16x16x32_bf16 v[60:63], v[146:149], v[162:165], v[60:63]
	v_mfma_f32_16x16x32_bf16 v[56:59], v[154:157], v[162:165], v[56:59]
	v_mfma_f32_16x16x32_bf16 v[52:55], v[146:149], v[170:173], v[52:55]
	v_mfma_f32_16x16x32_bf16 v[48:51], v[154:157], v[170:173], v[48:51]
	v_mfma_f32_16x16x32_bf16 v[36:39], v[146:149], v[182:185], v[36:39]
	v_mfma_f32_16x16x32_bf16 v[32:35], v[154:157], v[182:185], v[32:35]
	v_mfma_f32_16x16x32_bf16 v[20:23], v[146:149], v[190:193], v[20:23]
	v_mfma_f32_16x16x32_bf16 v[16:19], v[154:157], v[190:193], v[16:19]
	s_barrier
; __device__ __forceinline__ unsigned cvtpk(float lo, float hi) { const f32x2 v = (f32x2){lo, hi}; const bf16v2 b = __builtin_convertvector(v, bf16v2); return __builtin_bit_cast(unsigned, b); }
; #define PG8_STAGE(bufoff, gbase, voff) do { _Pragma("unroll") for (int _i = 0; _i < 2; ++_i) \
;         __builtin_amdgcn_global_load_lds((const unsigned*)((const char*)(gbase) + (voff)[_i]), (PG8_LAS unsigned*)(lds + (bufoff) + ldsw + _i * 8192), 16, 0, 0); } while (0)
; #define PG8_MMA(ai, bj, At, Bt) do { __builtin_amdgcn_s_setprio(1); _Pragma("unroll") for (int m = 0; m < 4; ++m) _Pragma("unroll") for (int n = 0; n < 2; ++n) _Pragma("unroll") for (int k = 0; k < 2; ++k) \
;         acc[ai][bj][m][n] = __builtin_amdgcn_mfma_f32_16x16x32_bf16(Bt[n][k], At[m][k], acc[ai][bj][m][n], 0, 0, 0); __builtin_amdgcn_s_setprio(0); } while (0)
; #define PG8_WAIT_V(n) asm volatile("s_waitcnt vmcnt(" #n ")" ::: "memory")
; #define PG8_BAR __builtin_amdgcn_s_barrier()
; template <class Epi, class Sched>
; __device__ __forceinline__ void gemm_phase(PG8_LAS unsigned char* lds, const Gemm g, const Sched& S, const Epi& E) {
;     ...
;             PG8_STAGE(PG8_SB(1, 1), b3 + hstep, voffB);
;             PG8_WAIT_V(6); PG8_BAR; PG8_MMA(1, 1, At, B1); PG8_BAR;
;         }
;         if constexpr (!Epi::AFTER_DRAIN) { E(acc, cur, wr, wc, fr, fq); S.done(cur); }
;     __device__ __forceinline__ void operator()(const f32x4 (&acc)[2][2][4][2], const pg8::Unit& u, int wr, int wc, int fr, int fq) const {
;         const int row0 = u.pm * 256 + wr * 64 + fr, col0 = u.pn * 256 + wc * 32 + 8 * fq;
; #pragma unroll
;         for (int ai = 0; ai < 2; ++ai)
; #pragma unroll
;             for (int m = 0; m < 4; ++m) { bf16_t* rowp = O + (size_t)(row0 + ai * 128 + m * 16) * ldc + col0;
; #pragma unroll
;                 for (int bj = 0; bj < 2; ++bj) { const f32x4 v0 = acc[ai][bj][m][0], v1 = acc[ai][bj][m][1];
;                     u32x4 w; w.x = cvtpk(v0[0], v0[1]); w.y = cvtpk(v0[2], v0[3]); w.z = cvtpk(v1[0], v1[1]); w.w = cvtpk(v1[2], v1[3]);
;                     *(u32x4*)(rowp + bj * 128) = w; } }
	s_add_i32 m0, s18, 0x1c000
	s_add_u32 s8, s12, 0xb0080
	s_addc_u32 s9, s13, 0
	global_load_lds_dwordx4 v176, s[8:9]
	s_add_i32 m0, s18, 0x1e000
	s_nop 0
	global_load_lds_dwordx4 v128, s[8:9]
	s_waitcnt vmcnt(6)
	s_barrier
	v_mfma_f32_16x16x32_bf16 v[44:47], v[194:197], v[158:161], v[44:47]
	v_mfma_f32_16x16x32_bf16 v[40:43], v[202:205], v[158:161], v[40:43]
	v_mfma_f32_16x16x32_bf16 v[28:31], v[194:197], v[166:169], v[28:31]
	v_mfma_f32_16x16x32_bf16 v[24:27], v[202:205], v[166:169], v[24:27]
	v_mfma_f32_16x16x32_bf16 v[12:15], v[194:197], v[178:181], v[12:15]
	v_mfma_f32_16x16x32_bf16 v[8:11], v[202:205], v[178:181], v[8:11]
	v_mfma_f32_16x16x32_bf16 v[4:7], v[194:197], v[186:189], v[4:7]
	v_mfma_f32_16x16x32_bf16 v[0:3], v[202:205], v[186:189], v[0:3]
	v_mfma_f32_16x16x32_bf16 v[44:47], v[198:201], v[162:165], v[44:47]
	v_mfma_f32_16x16x32_bf16 v[40:43], v[206:209], v[162:165], v[40:43]
	v_mfma_f32_16x16x32_bf16 v[28:31], v[198:201], v[170:173], v[28:31]
	v_mfma_f32_16x16x32_bf16 v[24:27], v[206:209], v[170:173], v[24:27]
	v_mfma_f32_16x16x32_bf16 v[12:15], v[198:201], v[182:185], v[12:15]
	v_mfma_f32_16x16x32_bf16 v[8:11], v[206:209], v[182:185], v[8:11]
	v_mfma_f32_16x16x32_bf16 v[4:7], v[198:201], v[190:193], v[4:7]
	v_mfma_f32_16x16x32_bf16 v[0:3], v[206:209], v[190:193], v[0:3]
	s_add_i32 s45, s45, 2
	s_add_u32 s43, s43, 0x100
	s_addc_u32 s44, s44, 0
	s_cmp_gt_u32 s45, 41
	s_mov_b64 s[8:9], s[10:11]
	s_barrier
	s_cbranch_scc0 .LBB0_96
	v_lshl_add_u32 v142, s29, 8, v138
	v_lshl_or_b32 v144, s34, 8, v140
	v_ashrrev_i32_e32 v143, 31, v142
	v_readlane_b32 s8, v253, 18
	v_cvt_pk_bf16_f32 v108, v108, v109
	v_cvt_pk_bf16_f32 v109, v110, v111
	v_cvt_pk_bf16_f32 v110, v104, v105
	v_or_b32_e32 v104, 16, v142
	v_cvt_pk_bf16_f32 v92, v92, v93
	v_cvt_pk_bf16_f32 v93, v94, v95
	v_cvt_pk_bf16_f32 v94, v88, v89
	v_or_b32_e32 v88, 32, v142
	v_cvt_pk_bf16_f32 v76, v76, v77
	v_cvt_pk_bf16_f32 v77, v78, v79
	v_cvt_pk_bf16_f32 v78, v72, v73
	v_or_b32_e32 v72, 48, v142
	v_ashrrev_i32_e32 v145, 31, v144
	v_lshlrev_b64 v[146:147], 11, v[142:143]
	v_readlane_b32 s9, v253, 19
	v_ashrrev_i32_e32 v105, 31, v104
	v_ashrrev_i32_e32 v89, 31, v88
	v_ashrrev_i32_e32 v73, 31, v72
	v_lshl_add_u64 v[146:147], s[8:9], 0, v[146:147]
	v_lshlrev_b64 v[144:145], 1, v[144:145]
	v_lshlrev_b64 v[104:105], 11, v[104:105]
	v_lshlrev_b64 v[88:89], 11, v[88:89]
	v_lshlrev_b64 v[72:73], 11, v[72:73]
	v_lshl_add_u64 v[146:147], v[146:147], 0, v[144:145]
	v_lshl_add_u64 v[104:105], s[8:9], 0, v[104:105]
	v_lshl_add_u64 v[88:89], s[8:9], 0, v[88:89]
	v_lshl_add_u64 v[72:73], s[8:9], 0, v[72:73]
	s_mov_b64 s[8:9], 0x40000
	v_cvt_pk_bf16_f32 v68, v68, v69
	v_cvt_pk_bf16_f32 v69, v70, v71
	v_cvt_pk_bf16_f32 v70, v64, v65
	v_lshl_add_u64 v[64:65], v[146:147], 0, s[8:9]
	v_cvt_pk_bf16_f32 v60, v60, v61
	v_cvt_pk_bf16_f32 v61, v62, v63
	v_cvt_pk_bf16_f32 v62, v56, v57
	v_add_co_u32_e32 v56, vcc, s2, v146
	v_cvt_pk_bf16_f32 v44, v44, v45
	v_cvt_pk_bf16_f32 v45, v46, v47
	v_cvt_pk_bf16_f32 v46, v40, v41
	v_cvt_pk_bf16_f32 v47, v42, v43
	s_mov_b64 s[8:9], 0x48000
	v_addc_co_u32_e32 v57, vcc, 0, v147, vcc
	global_store_dwordx4 v[64:65], v[44:47], off offset:256
	v_cvt_pk_bf16_f32 v28, v28, v29
	v_cvt_pk_bf16_f32 v29, v30, v31
	v_lshl_add_u64 v[44:45], v[146:147], 0, s[8:9]
	s_mov_b32 s8, 0x48000
	v_add_co_u32_e32 v46, vcc, s8, v146
	v_cvt_pk_bf16_f32 v30, v24, v25
	v_cvt_pk_bf16_f32 v31, v26, v27
	s_mov_b64 s[8:9], 0x50000
	v_addc_co_u32_e32 v47, vcc, 0, v147, vcc
	global_store_dwordx4 v[44:45], v[28:31], off offset:256
	v_cvt_pk_bf16_f32 v12, v12, v13
	v_cvt_pk_bf16_f32 v13, v14, v15
	v_lshl_add_u64 v[28:29], v[146:147], 0, s[8:9]
	s_mov_b32 s8, 0x50000
	v_add_co_u32_e32 v30, vcc, s8, v146
	v_cvt_pk_bf16_f32 v14, v8, v9
	v_cvt_pk_bf16_f32 v15, v10, v11
	s_mov_b64 s[8:9], 0x58000
	v_cvt_pk_bf16_f32 v111, v106, v107
	v_addc_co_u32_e32 v31, vcc, 0, v147, vcc
	global_store_dwordx4 v[28:29], v[12:15], off offset:256
	global_store_dwordx4 v[146:147], v[108:111], off offset:256
	v_cvt_pk_bf16_f32 v95, v90, v91
	v_lshl_add_u64 v[12:13], v[146:147], 0, s[8:9]
	s_mov_b32 s8, 0x58000
	v_lshl_add_u64 v[108:109], v[104:105], 0, v[144:145]
	v_add_co_u32_e32 v14, vcc, s8, v146
	global_store_dwordx4 v[108:109], v[92:95], off offset:256
	v_cvt_pk_bf16_f32 v79, v74, v75
	v_addc_co_u32_e32 v15, vcc, 0, v147, vcc
	v_lshl_add_u64 v[92:93], v[88:89], 0, v[144:145]
	v_cvt_pk_bf16_f32 v124, v124, v125
	v_cvt_pk_bf16_f32 v125, v126, v127
	v_cvt_pk_bf16_f32 v126, v120, v121
	v_cvt_pk_bf16_f32 v127, v122, v123
	v_cvt_pk_bf16_f32 v104, v116, v117
	v_cvt_pk_bf16_f32 v105, v118, v119
	v_cvt_pk_bf16_f32 v106, v112, v113
	v_cvt_pk_bf16_f32 v107, v114, v115
	v_cvt_pk_bf16_f32 v88, v100, v101
	v_cvt_pk_bf16_f32 v89, v102, v103
	v_cvt_pk_bf16_f32 v90, v96, v97
	v_cvt_pk_bf16_f32 v91, v98, v99
	global_store_dwordx4 v[92:93], v[76:79], off offset:256
	v_cvt_pk_bf16_f32 v74, v80, v81
	v_cvt_pk_bf16_f32 v75, v82, v83
	v_lshl_add_u64 v[76:77], v[72:73], 0, v[144:145]
	v_cvt_pk_bf16_f32 v72, v84, v85
	v_cvt_pk_bf16_f32 v73, v86, v87
	v_cvt_pk_bf16_f32 v71, v66, v67
	v_cvt_pk_bf16_f32 v63, v58, v59
	v_cvt_pk_bf16_f32 v40, v52, v53
	v_cvt_pk_bf16_f32 v41, v54, v55
	v_cvt_pk_bf16_f32 v42, v48, v49
	v_cvt_pk_bf16_f32 v43, v50, v51
	v_cvt_pk_bf16_f32 v24, v36, v37
	v_cvt_pk_bf16_f32 v25, v38, v39
	v_cvt_pk_bf16_f32 v26, v32, v33
	v_cvt_pk_bf16_f32 v27, v34, v35
	v_cvt_pk_bf16_f32 v8, v20, v21
	v_cvt_pk_bf16_f32 v9, v22, v23
	v_cvt_pk_bf16_f32 v10, v16, v17
	v_cvt_pk_bf16_f32 v11, v18, v19
	v_cvt_pk_bf16_f32 v4, v4, v5
	v_cvt_pk_bf16_f32 v5, v6, v7
	v_cvt_pk_bf16_f32 v6, v0, v1
	v_cvt_pk_bf16_f32 v7, v2, v3
	s_and_b64 vcc, exec, s[38:39]
	s_mov_b32 s34, s40
	s_mov_b32 s29, s41
	s_mov_b64 s[10:11], s[4:5]
	s_mov_b64 s[8:9], s[0:1]
	global_store_dwordx4 v[146:147], v[124:127], off
	global_store_dwordx4 v[108:109], v[104:107], off
	global_store_dwordx4 v[92:93], v[88:91], off
	global_store_dwordx4 v[76:77], v[72:75], off
	global_store_dwordx4 v[76:77], v[68:71], off offset:256
	global_store_dwordx4 v[56:57], v[60:63], off
	global_store_dwordx4 v[46:47], v[40:43], off
	global_store_dwordx4 v[30:31], v[24:27], off
	global_store_dwordx4 v[14:15], v[8:11], off
	global_store_dwordx4 v[12:13], v[4:7], off offset:256
	s_cbranch_vccz .LBB0_89
	s_waitcnt vmcnt(0)
	s_cmpk_gt_u32 s17, 0xff
	v_readlane_b32 s2, v254, 59
	s_cbranch_scc1 .LBB0_100
	s_barrier

; #define PG8_STAGE(bufoff, gbase, voff) do { _Pragma("unroll") for (int _i = 0; _i < 2; ++_i) \
;         __builtin_amdgcn_global_load_lds((const unsigned*)((const char*)(gbase) + (voff)[_i]), (PG8_LAS unsigned*)(lds + (bufoff) + ldsw + _i * 8192), 16, 0, 0); } while (0)
; #define PG8_LDA(dst, b, h) do { _Pragma("unroll") for (int m = 0; m < 4; ++m) _Pragma("unroll") for (int k = 0; k < 2; ++k) dst[m][k] = *(const PG8_LAS bf16x8*)(lds + PG8_SA(b, h) + aoff + m * 2048 + k * 1024); } while (0)
; #define PG8_LDB(dst, b, h) do { _Pragma("unroll") for (int n = 0; n < 2; ++n) _Pragma("unroll") for (int k = 0; k < 2; ++k) dst[n][k] = *(const PG8_LAS bf16x8*)(lds + PG8_SB(b, h) + boff + n * 2048 + k * 1024); } while (0)
; #define PG8_MMA(ai, bj, At, Bt) do { __builtin_amdgcn_s_setprio(1); _Pragma("unroll") for (int m = 0; m < 4; ++m) _Pragma("unroll") for (int n = 0; n < 2; ++n) _Pragma("unroll") for (int k = 0; k < 2; ++k) \
;         acc[ai][bj][m][n] = __builtin_amdgcn_mfma_f32_16x16x32_bf16(Bt[n][k], At[m][k], acc[ai][bj][m][n], 0, 0, 0); __builtin_amdgcn_s_setprio(0); } while (0)
; #define PG8_WAIT_V(n) asm volatile("s_waitcnt vmcnt(" #n ")" ::: "memory")
; template <class Epi, class Sched>
; __device__ __forceinline__ void gemm_phase(PG8_LAS unsigned char* lds, const Gemm g, const Sched& S, const Epi& E) {
;     ...
;         for (int t = 0; t < nt; t += 2) {
;             const bool last = (t == nt - 2);
;             const char* a1 = cA + (size_t)(t + 1) * kstep;
;             const char* a2 = last ? nA : cA + (size_t)(t + 2) * kstep; const char* b2 = last ? nB : cB + (size_t)(t + 2) * kstep;
;             const char* a3 = a2 + kstep; const char* b3 = b2 + kstep;
;             if (last && has_next) S.a_ready(nxt);
;             PG8_LDB(B0, 0, 0); PG8_SCHED; PG8_LDA(At, 0, 0); PG8_STAGE(PG8_SA(1, 1), a1 + hstep, voffA);
;             PG8_WAIT_L(8); PG8_BAR; PG8_WAIT_L(0); PG8_MMA(0, 0, At, B0); PG8_BAR; PG8_SCHED;
;             PG8_LDB(B1, 0, 1); PG8_STAGE(PG8_SB(0, 0), b2, voffB);
;             PG8_BAR; PG8_WAIT_L(0); PG8_MMA(0, 1, At, B1); PG8_BAR;
;             PG8_LDA(At, 0, 1); PG8_STAGE(PG8_SA(0, 0), a2, voffA);
;             PG8_BAR; PG8_WAIT_L(0); PG8_MMA(1, 0, At, B0); PG8_BAR; PG8_SCHED;
;             PG8_STAGE(PG8_SB(0, 1), b2 + hstep, voffB);
;             PG8_WAIT_V(6); PG8_BAR; PG8_MMA(1, 1, At, B1); PG8_BAR;
.LBB0_114:
	s_add_u32 s14, s12, 0xfffc0080
	s_addc_u32 s15, s13, -1
	v_add_u32_e32 v154, 0x10000, v143
	ds_read_b128 v[138:141], v154
	ds_read_b128 v[146:149], v154 offset:1024
	ds_read_b128 v[150:153], v154 offset:2048
	ds_read_b128 v[154:157], v154 offset:3072
	s_cmp_eq_u32 s45, 12
	s_cselect_b32 s17, s5, s15
	s_cselect_b32 s16, s40, s14
	s_cselect_b32 s15, s1, s44
	s_cselect_b32 s14, s41, s43
	s_add_i32 m0, s11, 0xc000
	ds_read_b128 v[158:161], v145
	ds_read_b128 v[162:165], v145 offset:1024
	ds_read_b128 v[166:169], v145 offset:2048
	ds_read_b128 v[170:173], v145 offset:3072
	ds_read_b128 v[178:181], v145 offset:4096
	ds_read_b128 v[182:185], v145 offset:5120
	ds_read_b128 v[186:189], v145 offset:6144
	global_load_lds_dwordx4 v134, s[12:13]
	s_add_i32 m0, s11, 0xe000
	ds_read_b128 v[190:193], v145 offset:7168
	global_load_lds_dwordx4 v136, s[12:13]
	s_waitcnt lgkmcnt(8)
	s_barrier
	s_waitcnt lgkmcnt(0)
	v_mfma_f32_16x16x32_bf16 v[124:127], v[138:141], v[158:161], v[124:127]
	v_mfma_f32_16x16x32_bf16 v[116:119], v[150:153], v[158:161], v[116:119]
	v_mfma_f32_16x16x32_bf16 v[108:111], v[138:141], v[166:169], v[108:111]
	v_mfma_f32_16x16x32_bf16 v[100:103], v[150:153], v[166:169], v[100:103]
	v_mfma_f32_16x16x32_bf16 v[92:95], v[138:141], v[178:181], v[92:95]
	v_mfma_f32_16x16x32_bf16 v[84:87], v[150:153], v[178:181], v[84:87]
	v_mfma_f32_16x16x32_bf16 v[76:79], v[138:141], v[186:189], v[76:79]
	v_mfma_f32_16x16x32_bf16 v[68:71], v[150:153], v[186:189], v[68:71]
	v_mfma_f32_16x16x32_bf16 v[124:127], v[146:149], v[162:165], v[124:127]
	v_mfma_f32_16x16x32_bf16 v[116:119], v[154:157], v[162:165], v[116:119]
	v_mfma_f32_16x16x32_bf16 v[108:111], v[146:149], v[170:173], v[108:111]
	v_mfma_f32_16x16x32_bf16 v[100:103], v[154:157], v[170:173], v[100:103]
	v_mfma_f32_16x16x32_bf16 v[92:95], v[146:149], v[182:185], v[92:95]
	v_mfma_f32_16x16x32_bf16 v[84:87], v[154:157], v[182:185], v[84:87]
	v_mfma_f32_16x16x32_bf16 v[76:79], v[146:149], v[190:193], v[76:79]
	v_mfma_f32_16x16x32_bf16 v[68:71], v[154:157], v[190:193], v[68:71]
	s_barrier
	s_add_i32 s48, 0, 0x14000
	v_add_u32_e32 v174, 0x14000, v143
	ds_read_b128 v[194:197], v174
	ds_read_b128 v[198:201], v174 offset:1024
	s_add_u32 s98, s14, 0x80
	s_addc_u32 s99, s15, 0
	s_add_i32 m0, s20, 0x10000
	ds_read_b128 v[202:205], v174 offset:2048
	global_load_lds_dwordx4 v176, s[14:15]
	s_add_i32 m0, s20, 0x12000
	ds_read_b128 v[206:209], v174 offset:3072
	global_load_lds_dwordx4 v128, s[14:15]
	s_barrier
	s_waitcnt lgkmcnt(0)
	v_mfma_f32_16x16x32_bf16 v[120:123], v[194:197], v[158:161], v[120:123]
	v_mfma_f32_16x16x32_bf16 v[112:115], v[202:205], v[158:161], v[112:115]
	v_mfma_f32_16x16x32_bf16 v[104:107], v[194:197], v[166:169], v[104:107]
	v_mfma_f32_16x16x32_bf16 v[96:99], v[202:205], v[166:169], v[96:99]
	v_mfma_f32_16x16x32_bf16 v[88:91], v[194:197], v[178:181], v[88:91]
	v_mfma_f32_16x16x32_bf16 v[80:83], v[202:205], v[178:181], v[80:83]
	v_mfma_f32_16x16x32_bf16 v[72:75], v[194:197], v[186:189], v[72:75]
	v_mfma_f32_16x16x32_bf16 v[64:67], v[202:205], v[186:189], v[64:67]
	v_mfma_f32_16x16x32_bf16 v[120:123], v[198:201], v[162:165], v[120:123]
	v_mfma_f32_16x16x32_bf16 v[112:115], v[206:209], v[162:165], v[112:115]
	v_mfma_f32_16x16x32_bf16 v[104:107], v[198:201], v[170:173], v[104:107]
	v_mfma_f32_16x16x32_bf16 v[96:99], v[206:209], v[170:173], v[96:99]
	v_mfma_f32_16x16x32_bf16 v[88:91], v[198:201], v[182:185], v[88:91]
	v_mfma_f32_16x16x32_bf16 v[80:83], v[206:209], v[182:185], v[80:83]
	v_mfma_f32_16x16x32_bf16 v[72:75], v[198:201], v[190:193], v[72:75]
	v_mfma_f32_16x16x32_bf16 v[64:67], v[206:209], v[190:193], v[64:67]
	s_mov_b32 m0, s11
	s_add_u32 s100, s16, 0x80
	s_addc_u32 s101, s17, 0
	s_barrier
	ds_read_b128 v[158:161], v145 offset:16384
	ds_read_b128 v[162:165], v145 offset:17408
	ds_read_b128 v[166:169], v145 offset:18432
	ds_read_b128 v[170:173], v145 offset:19456
	ds_read_b128 v[178:181], v145 offset:20480
	ds_read_b128 v[182:185], v145 offset:21504
	ds_read_b128 v[186:189], v145 offset:22528
	global_load_lds_dwordx4 v132, s[16:17]
	s_mov_b32 m0, s22
	ds_read_b128 v[190:193], v145 offset:23552
	global_load_lds_dwordx4 v130, s[16:17]
	s_barrier
	s_waitcnt lgkmcnt(0)
	v_mfma_f32_16x16x32_bf16 v[60:63], v[138:141], v[158:161], v[60:63]
	v_mfma_f32_16x16x32_bf16 v[52:55], v[150:153], v[158:161], v[52:55]
	v_mfma_f32_16x16x32_bf16 v[44:47], v[138:141], v[166:169], v[44:47]
	v_mfma_f32_16x16x32_bf16 v[36:39], v[150:153], v[166:169], v[36:39]
	v_mfma_f32_16x16x32_bf16 v[28:31], v[138:141], v[178:181], v[28:31]
	v_mfma_f32_16x16x32_bf16 v[20:23], v[150:153], v[178:181], v[20:23]
	v_mfma_f32_16x16x32_bf16 v[12:15], v[138:141], v[186:189], v[12:15]
	v_mfma_f32_16x16x32_bf16 v[4:7], v[150:153], v[186:189], v[4:7]
	v_mfma_f32_16x16x32_bf16 v[60:63], v[146:149], v[162:165], v[60:63]
	v_mfma_f32_16x16x32_bf16 v[52:55], v[154:157], v[162:165], v[52:55]
	v_mfma_f32_16x16x32_bf16 v[44:47], v[146:149], v[170:173], v[44:47]
	v_mfma_f32_16x16x32_bf16 v[36:39], v[154:157], v[170:173], v[36:39]
	v_mfma_f32_16x16x32_bf16 v[28:31], v[146:149], v[182:185], v[28:31]
	v_mfma_f32_16x16x32_bf16 v[20:23], v[154:157], v[182:185], v[20:23]
	v_mfma_f32_16x16x32_bf16 v[12:15], v[146:149], v[190:193], v[12:15]
	v_mfma_f32_16x16x32_bf16 v[4:7], v[154:157], v[190:193], v[4:7]
	s_barrier
	s_add_i32 m0, s20, 0x14000
	s_add_u32 s46, s14, 0x40000
	s_addc_u32 s47, s15, 0
	global_load_lds_dwordx4 v176, s[46:47]
	s_add_i32 m0, s20, 0x16000
	s_nop 0
	global_load_lds_dwordx4 v128, s[46:47]
	s_waitcnt vmcnt(6)
	s_barrier
; #define PG8_STAGE(bufoff, gbase, voff) do { _Pragma("unroll") for (int _i = 0; _i < 2; ++_i) \
;         __builtin_amdgcn_global_load_lds((const unsigned*)((const char*)(gbase) + (voff)[_i]), (PG8_LAS unsigned*)(lds + (bufoff) + ldsw + _i * 8192), 16, 0, 0); } while (0)
; #define PG8_LDA(dst, b, h) do { _Pragma("unroll") for (int m = 0; m < 4; ++m) _Pragma("unroll") for (int k = 0; k < 2; ++k) dst[m][k] = *(const PG8_LAS bf16x8*)(lds + PG8_SA(b, h) + aoff + m * 2048 + k * 1024); } while (0)
; #define PG8_LDB(dst, b, h) do { _Pragma("unroll") for (int n = 0; n < 2; ++n) _Pragma("unroll") for (int k = 0; k < 2; ++k) dst[n][k] = *(const PG8_LAS bf16x8*)(lds + PG8_SB(b, h) + boff + n * 2048 + k * 1024); } while (0)
; #define PG8_MMA(ai, bj, At, Bt) do { __builtin_amdgcn_s_setprio(1); _Pragma("unroll") for (int m = 0; m < 4; ++m) _Pragma("unroll") for (int n = 0; n < 2; ++n) _Pragma("unroll") for (int k = 0; k < 2; ++k) \
;         acc[ai][bj][m][n] = __builtin_amdgcn_mfma_f32_16x16x32_bf16(Bt[n][k], At[m][k], acc[ai][bj][m][n], 0, 0, 0); __builtin_amdgcn_s_setprio(0); } while (0)
; #define PG8_WAIT_V(n) asm volatile("s_waitcnt vmcnt(" #n ")" ::: "memory")
; #define PG8_WAIT_L(n) asm volatile("s_waitcnt lgkmcnt(" #n ")" ::: "memory")
; #define PG8_BAR __builtin_amdgcn_s_barrier()
; #define PG8_SCHED __builtin_amdgcn_sched_barrier(0)
; template <class Epi, class Sched>
; __device__ __forceinline__ void gemm_phase(PG8_LAS unsigned char* lds, const Gemm g, const Sched& S, const Epi& E) {
;     ...
;             PG8_WAIT_V(6); PG8_BAR; PG8_MMA(1, 1, At, B1); PG8_BAR;
;             PG8_LDB(B0, 1, 0); PG8_SCHED; PG8_LDA(At, 1, 0); PG8_STAGE(PG8_SA(0, 1), a2 + hstep, voffA);
;             PG8_WAIT_L(8); PG8_BAR; PG8_WAIT_L(0); PG8_MMA(0, 0, At, B0); PG8_BAR; PG8_SCHED;
;             PG8_LDB(B1, 1, 1); PG8_STAGE(PG8_SB(1, 0), b3, voffB);
;             PG8_BAR; PG8_WAIT_L(0); PG8_MMA(0, 1, At, B1); PG8_BAR;
;             PG8_LDA(At, 1, 1); PG8_STAGE(PG8_SA(1, 0), a3, voffA);
;             PG8_BAR; PG8_WAIT_L(0); PG8_MMA(1, 0, At, B0); PG8_BAR; PG8_SCHED;
	v_mfma_f32_16x16x32_bf16 v[56:59], v[194:197], v[158:161], v[56:59]
	v_mfma_f32_16x16x32_bf16 v[48:51], v[202:205], v[158:161], v[48:51]
	v_mfma_f32_16x16x32_bf16 v[40:43], v[194:197], v[166:169], v[40:43]
	v_mfma_f32_16x16x32_bf16 v[32:35], v[202:205], v[166:169], v[32:35]
	v_mfma_f32_16x16x32_bf16 v[24:27], v[194:197], v[178:181], v[24:27]
	v_mfma_f32_16x16x32_bf16 v[16:19], v[202:205], v[178:181], v[16:19]
	v_mfma_f32_16x16x32_bf16 v[8:11], v[194:197], v[186:189], v[8:11]
	v_mfma_f32_16x16x32_bf16 v[0:3], v[202:205], v[186:189], v[0:3]
	v_mfma_f32_16x16x32_bf16 v[56:59], v[198:201], v[162:165], v[56:59]
	v_mfma_f32_16x16x32_bf16 v[48:51], v[206:209], v[162:165], v[48:51]
	v_mfma_f32_16x16x32_bf16 v[40:43], v[198:201], v[170:173], v[40:43]
	v_mfma_f32_16x16x32_bf16 v[32:35], v[206:209], v[170:173], v[32:35]
	v_mfma_f32_16x16x32_bf16 v[24:27], v[198:201], v[182:185], v[24:27]
	v_mfma_f32_16x16x32_bf16 v[16:19], v[206:209], v[182:185], v[16:19]
	v_mfma_f32_16x16x32_bf16 v[8:11], v[198:201], v[190:193], v[8:11]
	v_mfma_f32_16x16x32_bf16 v[0:3], v[206:209], v[190:193], v[0:3]
	v_add_u32_e32 v154, 0x18000, v143
	s_barrier
	ds_read_b128 v[138:141], v154
	ds_read_b128 v[146:149], v154 offset:1024
	ds_read_b128 v[150:153], v154 offset:2048
	ds_read_b128 v[154:157], v154 offset:3072
	s_add_u32 s16, s16, 0x40000
	s_addc_u32 s17, s17, 0
	s_mov_b32 m0, s23
	ds_read_b128 v[158:161], v145 offset:32768
	ds_read_b128 v[162:165], v145 offset:33792
	ds_read_b128 v[166:169], v145 offset:34816
	ds_read_b128 v[170:173], v145 offset:35840
	ds_read_b128 v[178:181], v145 offset:36864
	ds_read_b128 v[182:185], v145 offset:37888
	ds_read_b128 v[186:189], v145 offset:38912
	global_load_lds_dwordx4 v132, s[16:17]
	s_mov_b32 m0, s26
	ds_read_b128 v[190:193], v145 offset:39936
	global_load_lds_dwordx4 v130, s[16:17]
	s_waitcnt lgkmcnt(8)
	s_barrier
	s_waitcnt lgkmcnt(0)
	v_mfma_f32_16x16x32_bf16 v[124:127], v[138:141], v[158:161], v[124:127]
	v_mfma_f32_16x16x32_bf16 v[116:119], v[150:153], v[158:161], v[116:119]
	v_mfma_f32_16x16x32_bf16 v[108:111], v[138:141], v[166:169], v[108:111]
	v_mfma_f32_16x16x32_bf16 v[100:103], v[150:153], v[166:169], v[100:103]
	v_mfma_f32_16x16x32_bf16 v[92:95], v[138:141], v[178:181], v[92:95]
	v_mfma_f32_16x16x32_bf16 v[84:87], v[150:153], v[178:181], v[84:87]
	v_mfma_f32_16x16x32_bf16 v[76:79], v[138:141], v[186:189], v[76:79]
	v_mfma_f32_16x16x32_bf16 v[68:71], v[150:153], v[186:189], v[68:71]
	v_mfma_f32_16x16x32_bf16 v[124:127], v[146:149], v[162:165], v[124:127]
	v_mfma_f32_16x16x32_bf16 v[116:119], v[154:157], v[162:165], v[116:119]
	v_mfma_f32_16x16x32_bf16 v[108:111], v[146:149], v[170:173], v[108:111]
	v_mfma_f32_16x16x32_bf16 v[100:103], v[154:157], v[170:173], v[100:103]
	v_mfma_f32_16x16x32_bf16 v[92:95], v[146:149], v[182:185], v[92:95]
	v_mfma_f32_16x16x32_bf16 v[84:87], v[154:157], v[182:185], v[84:87]
	v_mfma_f32_16x16x32_bf16 v[76:79], v[146:149], v[190:193], v[76:79]
	v_mfma_f32_16x16x32_bf16 v[68:71], v[154:157], v[190:193], v[68:71]
	s_barrier
	v_add_u32_e32 v206, 0x1c000, v143
	s_add_i32 m0, s20, 0x18000
	ds_read_b128 v[194:197], v206
	ds_read_b128 v[198:201], v206 offset:1024
	ds_read_b128 v[202:205], v206 offset:2048
	global_load_lds_dwordx4 v176, s[98:99]
	s_add_i32 m0, s20, 0x1a000
	ds_read_b128 v[206:209], v206 offset:3072
	global_load_lds_dwordx4 v128, s[98:99]
	s_barrier
	s_waitcnt lgkmcnt(0)
	v_mfma_f32_16x16x32_bf16 v[120:123], v[194:197], v[158:161], v[120:123]
	v_mfma_f32_16x16x32_bf16 v[112:115], v[202:205], v[158:161], v[112:115]
	v_mfma_f32_16x16x32_bf16 v[104:107], v[194:197], v[166:169], v[104:107]
	v_mfma_f32_16x16x32_bf16 v[96:99], v[202:205], v[166:169], v[96:99]
	v_mfma_f32_16x16x32_bf16 v[88:91], v[194:197], v[178:181], v[88:91]
	v_mfma_f32_16x16x32_bf16 v[80:83], v[202:205], v[178:181], v[80:83]
	v_mfma_f32_16x16x32_bf16 v[72:75], v[194:197], v[186:189], v[72:75]
	v_mfma_f32_16x16x32_bf16 v[64:67], v[202:205], v[186:189], v[64:67]
	v_mfma_f32_16x16x32_bf16 v[120:123], v[198:201], v[162:165], v[120:123]
	v_mfma_f32_16x16x32_bf16 v[112:115], v[206:209], v[162:165], v[112:115]
	v_mfma_f32_16x16x32_bf16 v[104:107], v[198:201], v[170:173], v[104:107]
	v_mfma_f32_16x16x32_bf16 v[96:99], v[206:209], v[170:173], v[96:99]
	v_mfma_f32_16x16x32_bf16 v[88:91], v[198:201], v[182:185], v[88:91]
	v_mfma_f32_16x16x32_bf16 v[80:83], v[206:209], v[182:185], v[80:83]
	v_mfma_f32_16x16x32_bf16 v[72:75], v[198:201], v[190:193], v[72:75]
	v_mfma_f32_16x16x32_bf16 v[64:67], v[206:209], v[190:193], v[64:67]
	s_mov_b32 m0, s28
	s_barrier
	ds_read_b128 v[158:161], v145 offset:49152
	ds_read_b128 v[162:165], v145 offset:50176
	ds_read_b128 v[166:169], v145 offset:51200
	ds_read_b128 v[170:173], v145 offset:52224
	ds_read_b128 v[178:181], v145 offset:53248
	ds_read_b128 v[182:185], v145 offset:54272
	ds_read_b128 v[186:189], v145 offset:55296
	global_load_lds_dwordx4 v132, s[100:101]
	s_mov_b32 m0, s29
	ds_read_b128 v[190:193], v145 offset:56320
	global_load_lds_dwordx4 v130, s[100:101]
	s_barrier
	s_waitcnt lgkmcnt(0)
	v_mfma_f32_16x16x32_bf16 v[60:63], v[138:141], v[158:161], v[60:63]
	v_mfma_f32_16x16x32_bf16 v[52:55], v[150:153], v[158:161], v[52:55]
	v_mfma_f32_16x16x32_bf16 v[44:47], v[138:141], v[166:169], v[44:47]
	v_mfma_f32_16x16x32_bf16 v[36:39], v[150:153], v[166:169], v[36:39]
	v_mfma_f32_16x16x32_bf16 v[28:31], v[138:141], v[178:181], v[28:31]
	v_mfma_f32_16x16x32_bf16 v[20:23], v[150:153], v[178:181], v[20:23]
	v_mfma_f32_16x16x32_bf16 v[12:15], v[138:141], v[186:189], v[12:15]
	v_mfma_f32_16x16x32_bf16 v[4:7], v[150:153], v[186:189], v[4:7]
	v_mfma_f32_16x16x32_bf16 v[60:63], v[146:149], v[162:165], v[60:63]
	v_mfma_f32_16x16x32_bf16 v[52:55], v[154:157], v[162:165], v[52:55]
	v_mfma_f32_16x16x32_bf16 v[44:47], v[146:149], v[170:173], v[44:47]
	v_mfma_f32_16x16x32_bf16 v[36:39], v[154:157], v[170:173], v[36:39]
	v_mfma_f32_16x16x32_bf16 v[28:31], v[146:149], v[182:185], v[28:31]
	v_mfma_f32_16x16x32_bf16 v[20:23], v[154:157], v[182:185], v[20:23]
	v_mfma_f32_16x16x32_bf16 v[12:15], v[146:149], v[190:193], v[12:15]
	v_mfma_f32_16x16x32_bf16 v[4:7], v[154:157], v[190:193], v[4:7]
	s_barrier
; __device__ __forceinline__ unsigned cvtpk(float lo, float hi) { const f32x2 v = (f32x2){lo, hi}; const bf16v2 b = __builtin_convertvector(v, bf16v2); return __builtin_bit_cast(unsigned, b); }
; __device__ __forceinline__ float siluf_(float x) { return x * sigmoidf_(x); }
; #define PG8_STAGE(bufoff, gbase, voff) do { _Pragma("unroll") for (int _i = 0; _i < 2; ++_i) \
;         __builtin_amdgcn_global_load_lds((const unsigned*)((const char*)(gbase) + (voff)[_i]), (PG8_LAS unsigned*)(lds + (bufoff) + ldsw + _i * 8192), 16, 0, 0); } while (0)
; #define PG8_MMA(ai, bj, At, Bt) do { __builtin_amdgcn_s_setprio(1); _Pragma("unroll") for (int m = 0; m < 4; ++m) _Pragma("unroll") for (int n = 0; n < 2; ++n) _Pragma("unroll") for (int k = 0; k < 2; ++k) \
;         acc[ai][bj][m][n] = __builtin_amdgcn_mfma_f32_16x16x32_bf16(Bt[n][k], At[m][k], acc[ai][bj][m][n], 0, 0, 0); __builtin_amdgcn_s_setprio(0); } while (0)
; #define PG8_WAIT_V(n) asm volatile("s_waitcnt vmcnt(" #n ")" ::: "memory")
; #define PG8_BAR __builtin_amdgcn_s_barrier()
; template <class Epi, class Sched>
; __device__ __forceinline__ void gemm_phase(PG8_LAS unsigned char* lds, const Gemm g, const Sched& S, const Epi& E) {
;     ...
;             PG8_STAGE(PG8_SB(1, 1), b3 + hstep, voffB);
;             PG8_WAIT_V(6); PG8_BAR; PG8_MMA(1, 1, At, B1); PG8_BAR;
;     __device__ __forceinline__ void operator()(const f32x4 (&acc)[2][2][4][2], const pg8::Unit& u, int wr, int wc, int fr, int fq) const {
;         const int row0 = u.pm * 256 + wr * 64 + fr, col0 = u.pn * 128 + wc * 32 + 8 * fq;
; #pragma unroll
;         for (int ai = 0; ai < 2; ++ai)
; #pragma unroll
;             for (int m = 0; m < 4; ++m) { bf16_t* rowp = O + (size_t)(row0 + ai * 128 + m * 16) * ldc + col0;
;                 const f32x4 g0 = acc[ai][0][m][0], g1 = acc[ai][0][m][1], u0 = acc[ai][1][m][0], u1 = acc[ai][1][m][1];
;                 u32x4 w; w.x = cvtpk(siluf_(g0[0]) * u0[0], siluf_(g0[1]) * u0[1]); w.y = cvtpk(siluf_(g0[2]) * u0[2], siluf_(g0[3]) * u0[3]);
;                 w.z = cvtpk(siluf_(g1[0]) * u1[0], siluf_(g1[1]) * u1[1]); w.w = cvtpk(siluf_(g1[2]) * u1[2], siluf_(g1[3]) * u1[3]);
;                 *(u32x4*)rowp = w; }
	s_add_i32 m0, s20, 0x1c000
	s_add_u32 s14, s14, 0x40080
	s_addc_u32 s15, s15, 0
	global_load_lds_dwordx4 v176, s[14:15]
	s_add_i32 m0, s20, 0x1e000
	s_nop 0
	global_load_lds_dwordx4 v128, s[14:15]
	s_waitcnt vmcnt(6)
	s_barrier
	v_mfma_f32_16x16x32_bf16 v[56:59], v[194:197], v[158:161], v[56:59]
	v_mfma_f32_16x16x32_bf16 v[48:51], v[202:205], v[158:161], v[48:51]
	v_mfma_f32_16x16x32_bf16 v[40:43], v[194:197], v[166:169], v[40:43]
	v_mfma_f32_16x16x32_bf16 v[32:35], v[202:205], v[166:169], v[32:35]
	v_mfma_f32_16x16x32_bf16 v[24:27], v[194:197], v[178:181], v[24:27]
	v_mfma_f32_16x16x32_bf16 v[16:19], v[202:205], v[178:181], v[16:19]
	v_mfma_f32_16x16x32_bf16 v[8:11], v[194:197], v[186:189], v[8:11]
	v_mfma_f32_16x16x32_bf16 v[0:3], v[202:205], v[186:189], v[0:3]
	v_mfma_f32_16x16x32_bf16 v[56:59], v[198:201], v[162:165], v[56:59]
	v_mfma_f32_16x16x32_bf16 v[48:51], v[206:209], v[162:165], v[48:51]
	v_mfma_f32_16x16x32_bf16 v[40:43], v[198:201], v[170:173], v[40:43]
	v_mfma_f32_16x16x32_bf16 v[32:35], v[206:209], v[170:173], v[32:35]
	v_mfma_f32_16x16x32_bf16 v[24:27], v[198:201], v[182:185], v[24:27]
	v_mfma_f32_16x16x32_bf16 v[16:19], v[206:209], v[182:185], v[16:19]
	v_mfma_f32_16x16x32_bf16 v[8:11], v[198:201], v[190:193], v[8:11]
	v_mfma_f32_16x16x32_bf16 v[0:3], v[206:209], v[190:193], v[0:3]
	s_add_i32 s45, s45, 2
	s_add_u32 s12, s12, 0x100
	s_addc_u32 s13, s13, 0
	s_add_u32 s43, s43, 0x100
	s_addc_u32 s44, s44, 0
	s_cmp_gt_u32 s45, 13
	s_barrier
	s_cbranch_scc0 .LBB0_114
	v_mul_f32_e32 v147, 0xbfb8aa3b, v124
	v_exp_f32_e32 v147, v147
	v_readlane_b32 s12, v253, 16
	v_lshl_add_u32 v146, s10, 8, v142
	v_lshl_or_b32 v140, s34, 7, v144
	v_add_f32_e32 v147, 1.0, v147
	v_rcp_f32_e32 v150, v147
	v_mul_f32_e32 v147, 0xbfb8aa3b, v125
	v_exp_f32_e32 v147, v147
	v_readlane_b32 s13, v253, 17
	v_ashrrev_i32_e32 v141, 31, v140
	v_lshlrev_b64 v[140:141], 1, v[140:141]
	v_add_f32_e32 v147, 1.0, v147
	v_rcp_f32_e32 v151, v147
	v_mov_b64_e32 v[138:139], s[12:13]
	v_mad_i64_i32 v[148:149], s[12:13], v146, s81, v[138:139]
	v_pk_mul_f32 v[124:125], v[124:125], v[150:151]
	v_lshl_add_u64 v[148:149], v[148:149], 0, v[140:141]
	v_pk_mul_f32 v[120:121], v[124:125], v[120:121]
	s_and_b64 vcc, exec, s[38:39]
	v_cvt_pk_bf16_f32 v120, v120, v121
	v_mul_f32_e32 v121, 0xbfb8aa3b, v126
	v_exp_f32_e32 v121, v121
	s_mov_b32 s34, s0
	s_mov_b32 s10, s4
	s_mov_b64 s[14:15], s[8:9]
	v_add_f32_e32 v121, 1.0, v121
	v_rcp_f32_e32 v124, v121
	v_mul_f32_e32 v121, 0xbfb8aa3b, v127
	v_exp_f32_e32 v121, v121
	s_nop 0
	v_add_f32_e32 v121, 1.0, v121
	v_rcp_f32_e32 v125, v121
	s_nop 0
	v_pk_mul_f32 v[124:125], v[126:127], v[124:125]
	s_nop 0
	v_pk_mul_f32 v[122:123], v[124:125], v[122:123]
	s_nop 0
	v_cvt_pk_bf16_f32 v121, v122, v123
	v_mul_f32_e32 v122, 0xbfb8aa3b, v116
	v_mul_f32_e32 v123, 0xbfb8aa3b, v117
	v_exp_f32_e32 v122, v122
	v_exp_f32_e32 v123, v123
	v_add_f32_e32 v122, 1.0, v122
	v_add_f32_e32 v123, 1.0, v123
	v_rcp_f32_e32 v122, v122
	v_rcp_f32_e32 v123, v123
	s_nop 0
	v_pk_mul_f32 v[116:117], v[116:117], v[122:123]
	s_nop 0
	v_pk_mul_f32 v[112:113], v[116:117], v[112:113]
	s_nop 0
	v_cvt_pk_bf16_f32 v122, v112, v113
	v_mul_f32_e32 v112, 0xbfb8aa3b, v118
	v_mul_f32_e32 v113, 0xbfb8aa3b, v119
	v_exp_f32_e32 v112, v112
	v_exp_f32_e32 v113, v113
	v_add_f32_e32 v112, 1.0, v112
	v_add_f32_e32 v113, 1.0, v113
	v_rcp_f32_e32 v112, v112
	v_rcp_f32_e32 v113, v113
	s_nop 0
	v_pk_mul_f32 v[112:113], v[118:119], v[112:113]
	s_nop 0
	v_pk_mul_f32 v[112:113], v[112:113], v[114:115]
	v_mul_f32_e32 v114, 0xbfb8aa3b, v108
	v_mul_f32_e32 v115, 0xbfb8aa3b, v109
	v_exp_f32_e32 v114, v114
	v_exp_f32_e32 v115, v115
	v_cvt_pk_bf16_f32 v123, v112, v113
	v_or_b32_e32 v112, 16, v146
	v_add_f32_e32 v114, 1.0, v114
	v_add_f32_e32 v115, 1.0, v115
	v_rcp_f32_e32 v114, v114
	v_rcp_f32_e32 v115, v115
	v_mad_i64_i32 v[112:113], s[12:13], v112, s81, v[138:139]
	v_lshl_add_u64 v[112:113], v[112:113], 0, v[140:141]
	v_pk_mul_f32 v[108:109], v[108:109], v[114:115]
	global_store_dwordx4 v[148:149], v[120:123], off
	v_pk_mul_f32 v[104:105], v[108:109], v[104:105]
	s_nop 0
	v_cvt_pk_bf16_f32 v104, v104, v105
	v_mul_f32_e32 v105, 0xbfb8aa3b, v110
	v_exp_f32_e32 v105, v105
	s_nop 0
	v_add_f32_e32 v105, 1.0, v105
	v_rcp_f32_e32 v108, v105
	v_mul_f32_e32 v105, 0xbfb8aa3b, v111
	v_exp_f32_e32 v105, v105
	s_nop 0
	v_add_f32_e32 v105, 1.0, v105
	v_rcp_f32_e32 v109, v105
	s_nop 0
	v_pk_mul_f32 v[108:109], v[110:111], v[108:109]
	s_nop 0
	v_pk_mul_f32 v[106:107], v[108:109], v[106:107]
	s_nop 0
	v_cvt_pk_bf16_f32 v105, v106, v107
	v_mul_f32_e32 v106, 0xbfb8aa3b, v100
	v_mul_f32_e32 v107, 0xbfb8aa3b, v101
	v_exp_f32_e32 v106, v106
	v_exp_f32_e32 v107, v107
	v_add_f32_e32 v106, 1.0, v106
	v_add_f32_e32 v107, 1.0, v107
	v_rcp_f32_e32 v106, v106
	v_rcp_f32_e32 v107, v107
	s_nop 0
	v_pk_mul_f32 v[100:101], v[100:101], v[106:107]
	s_nop 0
	v_pk_mul_f32 v[96:97], v[100:101], v[96:97]
	s_nop 0
	v_cvt_pk_bf16_f32 v106, v96, v97
	v_mul_f32_e32 v96, 0xbfb8aa3b, v102
	v_mul_f32_e32 v97, 0xbfb8aa3b, v103
	v_exp_f32_e32 v96, v96
	v_exp_f32_e32 v97, v97
	v_add_f32_e32 v96, 1.0, v96
	v_add_f32_e32 v97, 1.0, v97
	v_rcp_f32_e32 v96, v96
	v_rcp_f32_e32 v97, v97
	s_nop 0
	v_pk_mul_f32 v[96:97], v[102:103], v[96:97]
	s_nop 0
	v_pk_mul_f32 v[96:97], v[96:97], v[98:99]
	v_mul_f32_e32 v98, 0xbfb8aa3b, v92
	v_mul_f32_e32 v99, 0xbfb8aa3b, v93
	v_exp_f32_e32 v98, v98
	v_exp_f32_e32 v99, v99
	v_cvt_pk_bf16_f32 v107, v96, v97
	v_or_b32_e32 v96, 32, v146
	v_add_f32_e32 v98, 1.0, v98
	v_add_f32_e32 v99, 1.0, v99
	v_rcp_f32_e32 v98, v98
	v_rcp_f32_e32 v99, v99
	v_mad_i64_i32 v[96:97], s[12:13], v96, s81, v[138:139]
	v_lshl_add_u64 v[96:97], v[96:97], 0, v[140:141]
; __device__ __forceinline__ unsigned cvtpk(float lo, float hi) { const f32x2 v = (f32x2){lo, hi}; const bf16v2 b = __builtin_convertvector(v, bf16v2); return __builtin_bit_cast(unsigned, b); }
; __device__ __forceinline__ float sigmoidf_(float x) { return __builtin_amdgcn_rcpf(1.0f + __expf(-x)); }
; __device__ __forceinline__ float siluf_(float x) { return x * sigmoidf_(x); }
;     __device__ __forceinline__ void operator()(const f32x4 (&acc)[2][2][4][2], const pg8::Unit& u, int wr, int wc, int fr, int fq) const {
;     ...
;             for (int m = 0; m < 4; ++m) { bf16_t* rowp = O + (size_t)(row0 + ai * 128 + m * 16) * ldc + col0;
;                 const f32x4 g0 = acc[ai][0][m][0], g1 = acc[ai][0][m][1], u0 = acc[ai][1][m][0], u1 = acc[ai][1][m][1];
;                 u32x4 w; w.x = cvtpk(siluf_(g0[0]) * u0[0], siluf_(g0[1]) * u0[1]); w.y = cvtpk(siluf_(g0[2]) * u0[2], siluf_(g0[3]) * u0[3]);
;                 w.z = cvtpk(siluf_(g1[0]) * u1[0], siluf_(g1[1]) * u1[1]); w.w = cvtpk(siluf_(g1[2]) * u1[2], siluf_(g1[3]) * u1[3]);
;                 *(u32x4*)rowp = w; }
	v_pk_mul_f32 v[92:93], v[92:93], v[98:99]
	global_store_dwordx4 v[112:113], v[104:107], off
	v_pk_mul_f32 v[88:89], v[92:93], v[88:89]
	s_nop 0
	v_cvt_pk_bf16_f32 v88, v88, v89
	v_mul_f32_e32 v89, 0xbfb8aa3b, v94
	v_exp_f32_e32 v89, v89
	s_nop 0
	v_add_f32_e32 v89, 1.0, v89
	v_rcp_f32_e32 v92, v89
	v_mul_f32_e32 v89, 0xbfb8aa3b, v95
	v_exp_f32_e32 v89, v89
	s_nop 0
	v_add_f32_e32 v89, 1.0, v89
	v_rcp_f32_e32 v93, v89
	s_nop 0
	v_pk_mul_f32 v[92:93], v[94:95], v[92:93]
	s_nop 0
	v_pk_mul_f32 v[90:91], v[92:93], v[90:91]
	s_nop 0
	v_cvt_pk_bf16_f32 v89, v90, v91
	v_mul_f32_e32 v90, 0xbfb8aa3b, v84
	v_mul_f32_e32 v91, 0xbfb8aa3b, v85
	v_exp_f32_e32 v90, v90
	v_exp_f32_e32 v91, v91
	v_add_f32_e32 v90, 1.0, v90
	v_add_f32_e32 v91, 1.0, v91
	v_rcp_f32_e32 v90, v90
	v_rcp_f32_e32 v91, v91
	s_nop 0
	v_pk_mul_f32 v[84:85], v[84:85], v[90:91]
	s_nop 0
	v_pk_mul_f32 v[80:81], v[84:85], v[80:81]
	s_nop 0
	v_cvt_pk_bf16_f32 v90, v80, v81
	v_mul_f32_e32 v80, 0xbfb8aa3b, v86
	v_mul_f32_e32 v81, 0xbfb8aa3b, v87
	v_exp_f32_e32 v80, v80
	v_exp_f32_e32 v81, v81
	v_add_f32_e32 v80, 1.0, v80
	v_add_f32_e32 v81, 1.0, v81
	v_rcp_f32_e32 v80, v80
	v_rcp_f32_e32 v81, v81
	s_nop 0
	v_pk_mul_f32 v[80:81], v[86:87], v[80:81]
	s_nop 0
	v_pk_mul_f32 v[80:81], v[80:81], v[82:83]
	v_mul_f32_e32 v82, 0xbfb8aa3b, v76
	v_mul_f32_e32 v83, 0xbfb8aa3b, v77
	v_exp_f32_e32 v82, v82
	v_exp_f32_e32 v83, v83
	v_cvt_pk_bf16_f32 v91, v80, v81
	v_or_b32_e32 v80, 48, v146
	v_add_f32_e32 v82, 1.0, v82
	v_add_f32_e32 v83, 1.0, v83
	v_rcp_f32_e32 v82, v82
	v_rcp_f32_e32 v83, v83
	v_mad_i64_i32 v[80:81], s[12:13], v80, s81, v[138:139]
	v_lshl_add_u64 v[80:81], v[80:81], 0, v[140:141]
	v_pk_mul_f32 v[76:77], v[76:77], v[82:83]
	global_store_dwordx4 v[96:97], v[88:91], off
	v_pk_mul_f32 v[72:73], v[76:77], v[72:73]
	s_nop 0
	v_cvt_pk_bf16_f32 v72, v72, v73
	v_mul_f32_e32 v73, 0xbfb8aa3b, v78
	v_exp_f32_e32 v73, v73
	s_nop 0
	v_add_f32_e32 v73, 1.0, v73
	v_rcp_f32_e32 v76, v73
	v_mul_f32_e32 v73, 0xbfb8aa3b, v79
	v_exp_f32_e32 v73, v73
	s_nop 0
	v_add_f32_e32 v73, 1.0, v73
	v_rcp_f32_e32 v77, v73
	s_nop 0
	v_pk_mul_f32 v[76:77], v[78:79], v[76:77]
	s_nop 0
	v_pk_mul_f32 v[74:75], v[76:77], v[74:75]
	s_nop 0
	v_cvt_pk_bf16_f32 v73, v74, v75
	v_mul_f32_e32 v74, 0xbfb8aa3b, v68
	v_mul_f32_e32 v75, 0xbfb8aa3b, v69
	v_exp_f32_e32 v74, v74
	v_exp_f32_e32 v75, v75
	v_add_f32_e32 v74, 1.0, v74
	v_add_f32_e32 v75, 1.0, v75
	v_rcp_f32_e32 v74, v74
	v_rcp_f32_e32 v75, v75
	s_nop 0
	v_pk_mul_f32 v[68:69], v[68:69], v[74:75]
	s_nop 0
	v_pk_mul_f32 v[64:65], v[68:69], v[64:65]
	s_nop 0
	v_cvt_pk_bf16_f32 v74, v64, v65
	v_mul_f32_e32 v64, 0xbfb8aa3b, v70
	v_mul_f32_e32 v65, 0xbfb8aa3b, v71
	v_exp_f32_e32 v64, v64
	v_exp_f32_e32 v65, v65
	v_add_f32_e32 v64, 1.0, v64
	v_add_f32_e32 v65, 1.0, v65
	v_rcp_f32_e32 v64, v64
	v_rcp_f32_e32 v65, v65
	s_nop 0
	v_pk_mul_f32 v[64:65], v[70:71], v[64:65]
	s_nop 0
	v_pk_mul_f32 v[64:65], v[64:65], v[66:67]
	v_mul_f32_e32 v66, 0xbfb8aa3b, v60
	v_mul_f32_e32 v67, 0xbfb8aa3b, v61
	v_exp_f32_e32 v66, v66
	v_exp_f32_e32 v67, v67
	v_cvt_pk_bf16_f32 v75, v64, v65
	v_add_u32_e32 v64, 0x80, v146
	v_add_f32_e32 v66, 1.0, v66
	v_add_f32_e32 v67, 1.0, v67
	v_rcp_f32_e32 v66, v66
	v_rcp_f32_e32 v67, v67
	v_mad_i64_i32 v[64:65], s[12:13], v64, s81, v[138:139]
	v_lshl_add_u64 v[64:65], v[64:65], 0, v[140:141]
	v_pk_mul_f32 v[60:61], v[60:61], v[66:67]
	global_store_dwordx4 v[80:81], v[72:75], off
	v_pk_mul_f32 v[56:57], v[60:61], v[56:57]
	s_nop 0
	v_cvt_pk_bf16_f32 v56, v56, v57
	v_mul_f32_e32 v57, 0xbfb8aa3b, v62
	v_exp_f32_e32 v57, v57
	s_nop 0
	v_add_f32_e32 v57, 1.0, v57
	v_rcp_f32_e32 v60, v57
	v_mul_f32_e32 v57, 0xbfb8aa3b, v63
	v_exp_f32_e32 v57, v57
	s_nop 0
	v_add_f32_e32 v57, 1.0, v57
	v_rcp_f32_e32 v61, v57
	s_nop 0
	v_pk_mul_f32 v[60:61], v[62:63], v[60:61]
	s_nop 0
	v_pk_mul_f32 v[58:59], v[60:61], v[58:59]
	s_nop 0
	v_cvt_pk_bf16_f32 v57, v58, v59
	v_mul_f32_e32 v58, 0xbfb8aa3b, v52
	v_mul_f32_e32 v59, 0xbfb8aa3b, v53
	v_exp_f32_e32 v58, v58
	v_exp_f32_e32 v59, v59
	v_add_f32_e32 v58, 1.0, v58
	v_add_f32_e32 v59, 1.0, v59
	v_rcp_f32_e32 v58, v58
	v_rcp_f32_e32 v59, v59
	s_nop 0
	v_pk_mul_f32 v[52:53], v[52:53], v[58:59]
	s_nop 0
	v_pk_mul_f32 v[48:49], v[52:53], v[48:49]
	s_nop 0
	v_cvt_pk_bf16_f32 v58, v48, v49
	v_mul_f32_e32 v48, 0xbfb8aa3b, v54
	v_mul_f32_e32 v49, 0xbfb8aa3b, v55
	v_exp_f32_e32 v48, v48
	v_exp_f32_e32 v49, v49
	v_add_f32_e32 v48, 1.0, v48
	v_add_f32_e32 v49, 1.0, v49
	v_rcp_f32_e32 v48, v48
	v_rcp_f32_e32 v49, v49
	s_nop 0
	v_pk_mul_f32 v[48:49], v[54:55], v[48:49]
	s_nop 0
	v_pk_mul_f32 v[48:49], v[48:49], v[50:51]
	v_mul_f32_e32 v50, 0xbfb8aa3b, v44
	v_mul_f32_e32 v51, 0xbfb8aa3b, v45
	v_exp_f32_e32 v50, v50
	v_exp_f32_e32 v51, v51
	v_cvt_pk_bf16_f32 v59, v48, v49
	v_add_u32_e32 v48, 0x90, v146
	v_add_f32_e32 v50, 1.0, v50
	v_add_f32_e32 v51, 1.0, v51
	v_rcp_f32_e32 v50, v50
	v_rcp_f32_e32 v51, v51
; __device__ __forceinline__ unsigned cvtpk(float lo, float hi) { const f32x2 v = (f32x2){lo, hi}; const bf16v2 b = __builtin_convertvector(v, bf16v2); return __builtin_bit_cast(unsigned, b); }
; __device__ __forceinline__ float siluf_(float x) { return x * sigmoidf_(x); }
; #define PG8_WAIT_V(n) asm volatile("s_waitcnt vmcnt(" #n ")" ::: "memory")
; #define PG8_BAR __builtin_amdgcn_s_barrier()
; template <class Epi, class Sched>
; __device__ __forceinline__ void gemm_phase(PG8_LAS unsigned char* lds, const Gemm g, const Sched& S, const Epi& E) {
;     ...
;         if (!has_next) break;
; #pragma unroll
;         for (int a = 0; a < 2; ++a)
; #pragma unroll
;             for (int b = 0; b < 2; ++b)
; #pragma unroll
;                 for (int m = 0; m < 4; ++m)
; #pragma unroll
;                     for (int n = 0; n < 2; ++n) acc[a][b][m][n] = (f32x4){0.f, 0.f, 0.f, 0.f};
;         cur = nxt; cA = nA; cB = nB; ++ui;
;     }
;     PG8_WAIT_V(0);
;     if (wr == 0) PG8_BAR;
;     PG8_BAR;
;     __device__ __forceinline__ void operator()(const f32x4 (&acc)[2][2][4][2], const pg8::Unit& u, int wr, int wc, int fr, int fq) const {
;     ...
;             for (int m = 0; m < 4; ++m) { bf16_t* rowp = O + (size_t)(row0 + ai * 128 + m * 16) * ldc + col0;
;                 const f32x4 g0 = acc[ai][0][m][0], g1 = acc[ai][0][m][1], u0 = acc[ai][1][m][0], u1 = acc[ai][1][m][1];
;                 u32x4 w; w.x = cvtpk(siluf_(g0[0]) * u0[0], siluf_(g0[1]) * u0[1]); w.y = cvtpk(siluf_(g0[2]) * u0[2], siluf_(g0[3]) * u0[3]);
;                 w.z = cvtpk(siluf_(g1[0]) * u1[0], siluf_(g1[1]) * u1[1]); w.w = cvtpk(siluf_(g1[2]) * u1[2], siluf_(g1[3]) * u1[3]);
;                 *(u32x4*)rowp = w; }
	v_mad_i64_i32 v[48:49], s[12:13], v48, s81, v[138:139]
	v_lshl_add_u64 v[48:49], v[48:49], 0, v[140:141]
	v_pk_mul_f32 v[44:45], v[44:45], v[50:51]
	global_store_dwordx4 v[64:65], v[56:59], off
	v_pk_mul_f32 v[40:41], v[44:45], v[40:41]
	s_nop 0
	v_cvt_pk_bf16_f32 v40, v40, v41
	v_mul_f32_e32 v41, 0xbfb8aa3b, v46
	v_exp_f32_e32 v41, v41
	s_nop 0
	v_add_f32_e32 v41, 1.0, v41
	v_rcp_f32_e32 v44, v41
	v_mul_f32_e32 v41, 0xbfb8aa3b, v47
	v_exp_f32_e32 v41, v41
	s_nop 0
	v_add_f32_e32 v41, 1.0, v41
	v_rcp_f32_e32 v45, v41
	s_nop 0
	v_pk_mul_f32 v[44:45], v[46:47], v[44:45]
	s_nop 0
	v_pk_mul_f32 v[42:43], v[44:45], v[42:43]
	s_nop 0
	v_cvt_pk_bf16_f32 v41, v42, v43
	v_mul_f32_e32 v42, 0xbfb8aa3b, v36
	v_mul_f32_e32 v43, 0xbfb8aa3b, v37
	v_exp_f32_e32 v42, v42
	v_exp_f32_e32 v43, v43
	v_add_f32_e32 v42, 1.0, v42
	v_add_f32_e32 v43, 1.0, v43
	v_rcp_f32_e32 v42, v42
	v_rcp_f32_e32 v43, v43
	s_nop 0
	v_pk_mul_f32 v[36:37], v[36:37], v[42:43]
	s_nop 0
	v_pk_mul_f32 v[32:33], v[36:37], v[32:33]
	s_nop 0
	v_cvt_pk_bf16_f32 v42, v32, v33
	v_mul_f32_e32 v32, 0xbfb8aa3b, v38
	v_mul_f32_e32 v33, 0xbfb8aa3b, v39
	v_exp_f32_e32 v32, v32
	v_exp_f32_e32 v33, v33
	v_add_f32_e32 v32, 1.0, v32
	v_add_f32_e32 v33, 1.0, v33
	v_rcp_f32_e32 v32, v32
	v_rcp_f32_e32 v33, v33
	s_nop 0
	v_pk_mul_f32 v[32:33], v[38:39], v[32:33]
	s_nop 0
	v_pk_mul_f32 v[32:33], v[32:33], v[34:35]
	v_mul_f32_e32 v34, 0xbfb8aa3b, v28
	v_mul_f32_e32 v35, 0xbfb8aa3b, v29
	v_exp_f32_e32 v34, v34
	v_exp_f32_e32 v35, v35
	v_cvt_pk_bf16_f32 v43, v32, v33
	v_add_u32_e32 v32, 0xa0, v146
	v_add_f32_e32 v34, 1.0, v34
	v_add_f32_e32 v35, 1.0, v35
	v_rcp_f32_e32 v34, v34
	v_rcp_f32_e32 v35, v35
	v_mad_i64_i32 v[32:33], s[12:13], v32, s81, v[138:139]
	v_lshl_add_u64 v[32:33], v[32:33], 0, v[140:141]
	v_pk_mul_f32 v[28:29], v[28:29], v[34:35]
	global_store_dwordx4 v[48:49], v[40:43], off
	v_pk_mul_f32 v[24:25], v[28:29], v[24:25]
	s_nop 0
	v_cvt_pk_bf16_f32 v24, v24, v25
	v_mul_f32_e32 v25, 0xbfb8aa3b, v30
	v_exp_f32_e32 v25, v25
	s_nop 0
	v_add_f32_e32 v25, 1.0, v25
	v_rcp_f32_e32 v28, v25
	v_mul_f32_e32 v25, 0xbfb8aa3b, v31
	v_exp_f32_e32 v25, v25
	s_nop 0
	v_add_f32_e32 v25, 1.0, v25
	v_rcp_f32_e32 v29, v25
	s_nop 0
	v_pk_mul_f32 v[28:29], v[30:31], v[28:29]
	s_nop 0
	v_pk_mul_f32 v[26:27], v[28:29], v[26:27]
	s_nop 0
	v_cvt_pk_bf16_f32 v25, v26, v27
	v_mul_f32_e32 v26, 0xbfb8aa3b, v20
	v_mul_f32_e32 v27, 0xbfb8aa3b, v21
	v_exp_f32_e32 v26, v26
	v_exp_f32_e32 v27, v27
	v_add_f32_e32 v26, 1.0, v26
	v_add_f32_e32 v27, 1.0, v27
	v_rcp_f32_e32 v26, v26
	v_rcp_f32_e32 v27, v27
	s_nop 0
	v_pk_mul_f32 v[20:21], v[20:21], v[26:27]
	s_nop 0
	v_pk_mul_f32 v[16:17], v[20:21], v[16:17]
	s_nop 0
	v_cvt_pk_bf16_f32 v26, v16, v17
	v_mul_f32_e32 v16, 0xbfb8aa3b, v22
	v_mul_f32_e32 v17, 0xbfb8aa3b, v23
	v_exp_f32_e32 v16, v16
	v_exp_f32_e32 v17, v17
	v_add_f32_e32 v16, 1.0, v16
	v_add_f32_e32 v17, 1.0, v17
	v_rcp_f32_e32 v16, v16
	v_rcp_f32_e32 v17, v17
	s_nop 0
	v_pk_mul_f32 v[16:17], v[22:23], v[16:17]
	s_nop 0
	v_pk_mul_f32 v[16:17], v[16:17], v[18:19]
	v_mul_f32_e32 v18, 0xbfb8aa3b, v12
	v_mul_f32_e32 v19, 0xbfb8aa3b, v13
	v_exp_f32_e32 v18, v18
	v_exp_f32_e32 v19, v19
	v_cvt_pk_bf16_f32 v27, v16, v17
	v_add_u32_e32 v16, 0xb0, v146
	v_add_f32_e32 v18, 1.0, v18
	v_add_f32_e32 v19, 1.0, v19
	v_rcp_f32_e32 v18, v18
	v_rcp_f32_e32 v19, v19
	v_mad_i64_i32 v[16:17], s[12:13], v16, s81, v[138:139]
	v_lshl_add_u64 v[16:17], v[16:17], 0, v[140:141]
	v_pk_mul_f32 v[12:13], v[12:13], v[18:19]
	s_mov_b64 s[12:13], s[6:7]
	v_pk_mul_f32 v[8:9], v[12:13], v[8:9]
	global_store_dwordx4 v[32:33], v[24:27], off
	v_cvt_pk_bf16_f32 v8, v8, v9
	v_mul_f32_e32 v9, 0xbfb8aa3b, v14
	v_exp_f32_e32 v9, v9
	s_nop 0
	v_add_f32_e32 v9, 1.0, v9
	v_rcp_f32_e32 v12, v9
	v_mul_f32_e32 v9, 0xbfb8aa3b, v15
	v_exp_f32_e32 v9, v9
	s_nop 0
	v_add_f32_e32 v9, 1.0, v9
	v_rcp_f32_e32 v13, v9
	s_nop 0
	v_pk_mul_f32 v[12:13], v[14:15], v[12:13]
	s_nop 0
	v_pk_mul_f32 v[10:11], v[12:13], v[10:11]
	s_nop 0
	v_cvt_pk_bf16_f32 v9, v10, v11
	v_mul_f32_e32 v10, 0xbfb8aa3b, v4
	v_mul_f32_e32 v11, 0xbfb8aa3b, v5
	v_exp_f32_e32 v10, v10
	v_exp_f32_e32 v11, v11
	v_add_f32_e32 v10, 1.0, v10
	v_add_f32_e32 v11, 1.0, v11
	v_rcp_f32_e32 v10, v10
	v_rcp_f32_e32 v11, v11
	s_nop 0
	v_pk_mul_f32 v[4:5], v[4:5], v[10:11]
	s_nop 0
	v_pk_mul_f32 v[0:1], v[4:5], v[0:1]
	s_nop 0
	v_cvt_pk_bf16_f32 v10, v0, v1
	v_mul_f32_e32 v0, 0xbfb8aa3b, v6
	v_mul_f32_e32 v1, 0xbfb8aa3b, v7
	v_exp_f32_e32 v0, v0
	v_exp_f32_e32 v1, v1
	v_add_f32_e32 v0, 1.0, v0
	v_add_f32_e32 v1, 1.0, v1
	v_rcp_f32_e32 v0, v0
	v_rcp_f32_e32 v1, v1
	s_nop 0
	v_pk_mul_f32 v[0:1], v[6:7], v[0:1]
	s_nop 0
	v_pk_mul_f32 v[0:1], v[0:1], v[2:3]
	s_nop 0
	v_cvt_pk_bf16_f32 v11, v0, v1
	global_store_dwordx4 v[16:17], v[8:11], off
	s_cbranch_vccz .LBB0_111
	s_waitcnt vmcnt(0)
	v_readlane_b32 s22, v255, 14
	s_cmpk_gt_u32 s19, 0xff
	v_readlane_b32 s23, v255, 15
	s_mov_b64 s[28:29], s[54:55]
	s_cbranch_scc1 .LBB0_118
	s_barrier

; #define PG8_STAGE(bufoff, gbase, voff) do { _Pragma("unroll") for (int _i = 0; _i < 2; ++_i) \
;         __builtin_amdgcn_global_load_lds((const unsigned*)((const char*)(gbase) + (voff)[_i]), (PG8_LAS unsigned*)(lds + (bufoff) + ldsw + _i * 8192), 16, 0, 0); } while (0)
; #define PG8_LDA(dst, b, h) do { _Pragma("unroll") for (int m = 0; m < 4; ++m) _Pragma("unroll") for (int k = 0; k < 2; ++k) dst[m][k] = *(const PG8_LAS bf16x8*)(lds + PG8_SA(b, h) + aoff + m * 2048 + k * 1024); } while (0)
; #define PG8_LDB(dst, b, h) do { _Pragma("unroll") for (int n = 0; n < 2; ++n) _Pragma("unroll") for (int k = 0; k < 2; ++k) dst[n][k] = *(const PG8_LAS bf16x8*)(lds + PG8_SB(b, h) + boff + n * 2048 + k * 1024); } while (0)
; #define PG8_MMA(ai, bj, At, Bt) do { __builtin_amdgcn_s_setprio(1); _Pragma("unroll") for (int m = 0; m < 4; ++m) _Pragma("unroll") for (int n = 0; n < 2; ++n) _Pragma("unroll") for (int k = 0; k < 2; ++k) \
;         acc[ai][bj][m][n] = __builtin_amdgcn_mfma_f32_16x16x32_bf16(Bt[n][k], At[m][k], acc[ai][bj][m][n], 0, 0, 0); __builtin_amdgcn_s_setprio(0); } while (0)
; #define PG8_WAIT_V(n) asm volatile("s_waitcnt vmcnt(" #n ")" ::: "memory")
; #define PG8_WAIT_L(n) asm volatile("s_waitcnt lgkmcnt(" #n ")" ::: "memory")
; #define PG8_BAR __builtin_amdgcn_s_barrier()
; #define PG8_SCHED __builtin_amdgcn_sched_barrier(0)
; template <class Epi, class Sched>
; __device__ __forceinline__ void gemm_phase(PG8_LAS unsigned char* lds, const Gemm g, const Sched& S, const Epi& E) {
;     ...
;             PG8_LDB(B0, 0, 0); PG8_SCHED; PG8_LDA(At, 0, 0); PG8_STAGE(PG8_SA(1, 1), a1 + hstep, voffA);
;             PG8_WAIT_L(8); PG8_BAR; PG8_WAIT_L(0); PG8_MMA(0, 0, At, B0); PG8_BAR; PG8_SCHED;
;             PG8_LDB(B1, 0, 1); PG8_STAGE(PG8_SB(0, 0), b2, voffB);
;             PG8_BAR; PG8_WAIT_L(0); PG8_MMA(0, 1, At, B1); PG8_BAR;
;             PG8_LDA(At, 0, 1); PG8_STAGE(PG8_SA(0, 0), a2, voffA);
;             PG8_BAR; PG8_WAIT_L(0); PG8_MMA(1, 0, At, B0); PG8_BAR; PG8_SCHED;
;             PG8_STAGE(PG8_SB(0, 1), b2 + hstep, voffB);
;             PG8_WAIT_V(6); PG8_BAR; PG8_MMA(1, 1, At, B1); PG8_BAR;
.LBB0_137:
	s_add_u32 s14, s12, 0xfffc0080
	s_addc_u32 s15, s13, -1
	v_add_u32_e32 v154, 0x10000, v139
	ds_read_b128 v[142:145], v154
	ds_read_b128 v[146:149], v154 offset:1024
	ds_read_b128 v[150:153], v154 offset:2048
	ds_read_b128 v[154:157], v154 offset:3072
	s_cmp_eq_u32 s45, 12
	s_cselect_b32 s17, s7, s15
	s_cselect_b32 s16, s40, s14
	s_cselect_b32 s15, s5, s44
	s_cselect_b32 s14, s41, s43
	s_add_i32 m0, s1, 0xc000
	ds_read_b128 v[158:161], v141
	ds_read_b128 v[162:165], v141 offset:1024
	ds_read_b128 v[166:169], v141 offset:2048
	ds_read_b128 v[170:173], v141 offset:3072
	ds_read_b128 v[178:181], v141 offset:4096
	ds_read_b128 v[182:185], v141 offset:5120
	ds_read_b128 v[186:189], v141 offset:6144
	global_load_lds_dwordx4 v134, s[12:13]
	s_add_i32 m0, s1, 0xe000
	ds_read_b128 v[190:193], v141 offset:7168
	global_load_lds_dwordx4 v136, s[12:13]
	s_waitcnt lgkmcnt(8)
	s_barrier
	s_waitcnt lgkmcnt(0)
	v_mfma_f32_16x16x32_bf16 v[124:127], v[142:145], v[158:161], v[124:127]
	v_mfma_f32_16x16x32_bf16 v[120:123], v[150:153], v[158:161], v[120:123]
	v_mfma_f32_16x16x32_bf16 v[116:119], v[142:145], v[166:169], v[116:119]
	v_mfma_f32_16x16x32_bf16 v[112:115], v[150:153], v[166:169], v[112:115]
	v_mfma_f32_16x16x32_bf16 v[100:103], v[142:145], v[178:181], v[100:103]
	v_mfma_f32_16x16x32_bf16 v[96:99], v[150:153], v[178:181], v[96:99]
	v_mfma_f32_16x16x32_bf16 v[84:87], v[142:145], v[186:189], v[84:87]
	v_mfma_f32_16x16x32_bf16 v[80:83], v[150:153], v[186:189], v[80:83]
	v_mfma_f32_16x16x32_bf16 v[124:127], v[146:149], v[162:165], v[124:127]
	v_mfma_f32_16x16x32_bf16 v[120:123], v[154:157], v[162:165], v[120:123]
	v_mfma_f32_16x16x32_bf16 v[116:119], v[146:149], v[170:173], v[116:119]
	v_mfma_f32_16x16x32_bf16 v[112:115], v[154:157], v[170:173], v[112:115]
	v_mfma_f32_16x16x32_bf16 v[100:103], v[146:149], v[182:185], v[100:103]
	v_mfma_f32_16x16x32_bf16 v[96:99], v[154:157], v[182:185], v[96:99]
	v_mfma_f32_16x16x32_bf16 v[84:87], v[146:149], v[190:193], v[84:87]
	v_mfma_f32_16x16x32_bf16 v[80:83], v[154:157], v[190:193], v[80:83]
	s_barrier
	s_add_i32 s48, 0, 0x14000
	v_add_u32_e32 v174, 0x14000, v139
	ds_read_b128 v[194:197], v174
	ds_read_b128 v[198:201], v174 offset:1024
	s_add_u32 s98, s14, 0x80
	s_addc_u32 s99, s15, 0
	s_add_i32 m0, s20, 0x10000
	ds_read_b128 v[202:205], v174 offset:2048
	global_load_lds_dwordx4 v176, s[14:15]
	s_add_i32 m0, s20, 0x12000
	ds_read_b128 v[206:209], v174 offset:3072
	global_load_lds_dwordx4 v128, s[14:15]
	s_barrier
	s_waitcnt lgkmcnt(0)
	v_mfma_f32_16x16x32_bf16 v[108:111], v[194:197], v[158:161], v[108:111]
	v_mfma_f32_16x16x32_bf16 v[104:107], v[202:205], v[158:161], v[104:107]
	v_mfma_f32_16x16x32_bf16 v[92:95], v[194:197], v[166:169], v[92:95]
	v_mfma_f32_16x16x32_bf16 v[88:91], v[202:205], v[166:169], v[88:91]
	v_mfma_f32_16x16x32_bf16 v[76:79], v[194:197], v[178:181], v[76:79]
	v_mfma_f32_16x16x32_bf16 v[72:75], v[202:205], v[178:181], v[72:75]
	v_mfma_f32_16x16x32_bf16 v[68:71], v[194:197], v[186:189], v[68:71]
	v_mfma_f32_16x16x32_bf16 v[64:67], v[202:205], v[186:189], v[64:67]
	v_mfma_f32_16x16x32_bf16 v[108:111], v[198:201], v[162:165], v[108:111]
	v_mfma_f32_16x16x32_bf16 v[104:107], v[206:209], v[162:165], v[104:107]
	v_mfma_f32_16x16x32_bf16 v[92:95], v[198:201], v[170:173], v[92:95]
	v_mfma_f32_16x16x32_bf16 v[88:91], v[206:209], v[170:173], v[88:91]
	v_mfma_f32_16x16x32_bf16 v[76:79], v[198:201], v[182:185], v[76:79]
	v_mfma_f32_16x16x32_bf16 v[72:75], v[206:209], v[182:185], v[72:75]
	v_mfma_f32_16x16x32_bf16 v[68:71], v[198:201], v[190:193], v[68:71]
	v_mfma_f32_16x16x32_bf16 v[64:67], v[206:209], v[190:193], v[64:67]
	s_mov_b32 m0, s1
	s_add_u32 s100, s16, 0x80
	s_addc_u32 s101, s17, 0
	s_barrier
	ds_read_b128 v[158:161], v141 offset:16384
	ds_read_b128 v[162:165], v141 offset:17408
	ds_read_b128 v[166:169], v141 offset:18432
	ds_read_b128 v[170:173], v141 offset:19456
	ds_read_b128 v[178:181], v141 offset:20480
	ds_read_b128 v[182:185], v141 offset:21504
	ds_read_b128 v[186:189], v141 offset:22528
	global_load_lds_dwordx4 v132, s[16:17]
	s_mov_b32 m0, s22
	ds_read_b128 v[190:193], v141 offset:23552
	global_load_lds_dwordx4 v130, s[16:17]
	s_barrier
	s_waitcnt lgkmcnt(0)
	v_mfma_f32_16x16x32_bf16 v[60:63], v[142:145], v[158:161], v[60:63]
	v_mfma_f32_16x16x32_bf16 v[56:59], v[150:153], v[158:161], v[56:59]
	v_mfma_f32_16x16x32_bf16 v[52:55], v[142:145], v[166:169], v[52:55]
	v_mfma_f32_16x16x32_bf16 v[48:51], v[150:153], v[166:169], v[48:51]
	v_mfma_f32_16x16x32_bf16 v[36:39], v[142:145], v[178:181], v[36:39]
	v_mfma_f32_16x16x32_bf16 v[32:35], v[150:153], v[178:181], v[32:35]
	v_mfma_f32_16x16x32_bf16 v[20:23], v[142:145], v[186:189], v[20:23]
	v_mfma_f32_16x16x32_bf16 v[16:19], v[150:153], v[186:189], v[16:19]
	v_mfma_f32_16x16x32_bf16 v[60:63], v[146:149], v[162:165], v[60:63]
	v_mfma_f32_16x16x32_bf16 v[56:59], v[154:157], v[162:165], v[56:59]
	v_mfma_f32_16x16x32_bf16 v[52:55], v[146:149], v[170:173], v[52:55]
	v_mfma_f32_16x16x32_bf16 v[48:51], v[154:157], v[170:173], v[48:51]
	v_mfma_f32_16x16x32_bf16 v[36:39], v[146:149], v[182:185], v[36:39]
	v_mfma_f32_16x16x32_bf16 v[32:35], v[154:157], v[182:185], v[32:35]
	v_mfma_f32_16x16x32_bf16 v[20:23], v[146:149], v[190:193], v[20:23]
	v_mfma_f32_16x16x32_bf16 v[16:19], v[154:157], v[190:193], v[16:19]
	s_barrier
	s_add_i32 m0, s20, 0x14000
	s_add_u32 s46, s14, 0x40000
	s_addc_u32 s47, s15, 0
	global_load_lds_dwordx4 v176, s[46:47]
	s_add_i32 m0, s20, 0x16000
	s_nop 0
	global_load_lds_dwordx4 v128, s[46:47]
	s_waitcnt vmcnt(6)
	s_barrier
; #define PG8_STAGE(bufoff, gbase, voff) do { _Pragma("unroll") for (int _i = 0; _i < 2; ++_i) \
;         __builtin_amdgcn_global_load_lds((const unsigned*)((const char*)(gbase) + (voff)[_i]), (PG8_LAS unsigned*)(lds + (bufoff) + ldsw + _i * 8192), 16, 0, 0); } while (0)
; #define PG8_LDA(dst, b, h) do { _Pragma("unroll") for (int m = 0; m < 4; ++m) _Pragma("unroll") for (int k = 0; k < 2; ++k) dst[m][k] = *(const PG8_LAS bf16x8*)(lds + PG8_SA(b, h) + aoff + m * 2048 + k * 1024); } while (0)
; #define PG8_LDB(dst, b, h) do { _Pragma("unroll") for (int n = 0; n < 2; ++n) _Pragma("unroll") for (int k = 0; k < 2; ++k) dst[n][k] = *(const PG8_LAS bf16x8*)(lds + PG8_SB(b, h) + boff + n * 2048 + k * 1024); } while (0)
; #define PG8_MMA(ai, bj, At, Bt) do { __builtin_amdgcn_s_setprio(1); _Pragma("unroll") for (int m = 0; m < 4; ++m) _Pragma("unroll") for (int n = 0; n < 2; ++n) _Pragma("unroll") for (int k = 0; k < 2; ++k) \
;         acc[ai][bj][m][n] = __builtin_amdgcn_mfma_f32_16x16x32_bf16(Bt[n][k], At[m][k], acc[ai][bj][m][n], 0, 0, 0); __builtin_amdgcn_s_setprio(0); } while (0)
; #define PG8_WAIT_V(n) asm volatile("s_waitcnt vmcnt(" #n ")" ::: "memory")
; #define PG8_WAIT_L(n) asm volatile("s_waitcnt lgkmcnt(" #n ")" ::: "memory")
; #define PG8_BAR __builtin_amdgcn_s_barrier()
; #define PG8_SCHED __builtin_amdgcn_sched_barrier(0)
; template <class Epi, class Sched>
; __device__ __forceinline__ void gemm_phase(PG8_LAS unsigned char* lds, const Gemm g, const Sched& S, const Epi& E) {
;     ...
;             PG8_WAIT_V(6); PG8_BAR; PG8_MMA(1, 1, At, B1); PG8_BAR;
;             PG8_LDB(B0, 1, 0); PG8_SCHED; PG8_LDA(At, 1, 0); PG8_STAGE(PG8_SA(0, 1), a2 + hstep, voffA);
;             PG8_WAIT_L(8); PG8_BAR; PG8_WAIT_L(0); PG8_MMA(0, 0, At, B0); PG8_BAR; PG8_SCHED;
;             PG8_LDB(B1, 1, 1); PG8_STAGE(PG8_SB(1, 0), b3, voffB);
;             PG8_BAR; PG8_WAIT_L(0); PG8_MMA(0, 1, At, B1); PG8_BAR;
;             PG8_LDA(At, 1, 1); PG8_STAGE(PG8_SA(1, 0), a3, voffA);
;             PG8_BAR; PG8_WAIT_L(0); PG8_MMA(1, 0, At, B0); PG8_BAR; PG8_SCHED;
	v_mfma_f32_16x16x32_bf16 v[44:47], v[194:197], v[158:161], v[44:47]
	v_mfma_f32_16x16x32_bf16 v[40:43], v[202:205], v[158:161], v[40:43]
	v_mfma_f32_16x16x32_bf16 v[28:31], v[194:197], v[166:169], v[28:31]
	v_mfma_f32_16x16x32_bf16 v[24:27], v[202:205], v[166:169], v[24:27]
	v_mfma_f32_16x16x32_bf16 v[12:15], v[194:197], v[178:181], v[12:15]
	v_mfma_f32_16x16x32_bf16 v[8:11], v[202:205], v[178:181], v[8:11]
	v_mfma_f32_16x16x32_bf16 v[4:7], v[194:197], v[186:189], v[4:7]
	v_mfma_f32_16x16x32_bf16 v[0:3], v[202:205], v[186:189], v[0:3]
	v_mfma_f32_16x16x32_bf16 v[44:47], v[198:201], v[162:165], v[44:47]
	v_mfma_f32_16x16x32_bf16 v[40:43], v[206:209], v[162:165], v[40:43]
	v_mfma_f32_16x16x32_bf16 v[28:31], v[198:201], v[170:173], v[28:31]
	v_mfma_f32_16x16x32_bf16 v[24:27], v[206:209], v[170:173], v[24:27]
	v_mfma_f32_16x16x32_bf16 v[12:15], v[198:201], v[182:185], v[12:15]
	v_mfma_f32_16x16x32_bf16 v[8:11], v[206:209], v[182:185], v[8:11]
	v_mfma_f32_16x16x32_bf16 v[4:7], v[198:201], v[190:193], v[4:7]
	v_mfma_f32_16x16x32_bf16 v[0:3], v[206:209], v[190:193], v[0:3]
	v_add_u32_e32 v154, 0x18000, v139
	s_barrier
	ds_read_b128 v[142:145], v154
	ds_read_b128 v[146:149], v154 offset:1024
	ds_read_b128 v[150:153], v154 offset:2048
	ds_read_b128 v[154:157], v154 offset:3072
	s_add_u32 s16, s16, 0x40000
	s_addc_u32 s17, s17, 0
	s_mov_b32 m0, s23
	ds_read_b128 v[158:161], v141 offset:32768
	ds_read_b128 v[162:165], v141 offset:33792
	ds_read_b128 v[166:169], v141 offset:34816
	ds_read_b128 v[170:173], v141 offset:35840
	ds_read_b128 v[178:181], v141 offset:36864
	ds_read_b128 v[182:185], v141 offset:37888
	ds_read_b128 v[186:189], v141 offset:38912
	global_load_lds_dwordx4 v132, s[16:17]
	s_mov_b32 m0, s26
	ds_read_b128 v[190:193], v141 offset:39936
	global_load_lds_dwordx4 v130, s[16:17]
	s_waitcnt lgkmcnt(8)
	s_barrier
	s_waitcnt lgkmcnt(0)
	v_mfma_f32_16x16x32_bf16 v[124:127], v[142:145], v[158:161], v[124:127]
	v_mfma_f32_16x16x32_bf16 v[120:123], v[150:153], v[158:161], v[120:123]
	v_mfma_f32_16x16x32_bf16 v[116:119], v[142:145], v[166:169], v[116:119]
	v_mfma_f32_16x16x32_bf16 v[112:115], v[150:153], v[166:169], v[112:115]
	v_mfma_f32_16x16x32_bf16 v[100:103], v[142:145], v[178:181], v[100:103]
	v_mfma_f32_16x16x32_bf16 v[96:99], v[150:153], v[178:181], v[96:99]
	v_mfma_f32_16x16x32_bf16 v[84:87], v[142:145], v[186:189], v[84:87]
	v_mfma_f32_16x16x32_bf16 v[80:83], v[150:153], v[186:189], v[80:83]
	v_mfma_f32_16x16x32_bf16 v[124:127], v[146:149], v[162:165], v[124:127]
	v_mfma_f32_16x16x32_bf16 v[120:123], v[154:157], v[162:165], v[120:123]
	v_mfma_f32_16x16x32_bf16 v[116:119], v[146:149], v[170:173], v[116:119]
	v_mfma_f32_16x16x32_bf16 v[112:115], v[154:157], v[170:173], v[112:115]
	v_mfma_f32_16x16x32_bf16 v[100:103], v[146:149], v[182:185], v[100:103]
	v_mfma_f32_16x16x32_bf16 v[96:99], v[154:157], v[182:185], v[96:99]
	v_mfma_f32_16x16x32_bf16 v[84:87], v[146:149], v[190:193], v[84:87]
	v_mfma_f32_16x16x32_bf16 v[80:83], v[154:157], v[190:193], v[80:83]
	s_barrier
	v_add_u32_e32 v206, 0x1c000, v139
	s_add_i32 m0, s20, 0x18000
	ds_read_b128 v[194:197], v206
	ds_read_b128 v[198:201], v206 offset:1024
	ds_read_b128 v[202:205], v206 offset:2048
	global_load_lds_dwordx4 v176, s[98:99]
	s_add_i32 m0, s20, 0x1a000
	ds_read_b128 v[206:209], v206 offset:3072
	global_load_lds_dwordx4 v128, s[98:99]
	s_barrier
	s_waitcnt lgkmcnt(0)
	v_mfma_f32_16x16x32_bf16 v[108:111], v[194:197], v[158:161], v[108:111]
	v_mfma_f32_16x16x32_bf16 v[104:107], v[202:205], v[158:161], v[104:107]
	v_mfma_f32_16x16x32_bf16 v[92:95], v[194:197], v[166:169], v[92:95]
	v_mfma_f32_16x16x32_bf16 v[88:91], v[202:205], v[166:169], v[88:91]
	v_mfma_f32_16x16x32_bf16 v[76:79], v[194:197], v[178:181], v[76:79]
	v_mfma_f32_16x16x32_bf16 v[72:75], v[202:205], v[178:181], v[72:75]
	v_mfma_f32_16x16x32_bf16 v[68:71], v[194:197], v[186:189], v[68:71]
	v_mfma_f32_16x16x32_bf16 v[64:67], v[202:205], v[186:189], v[64:67]
	v_mfma_f32_16x16x32_bf16 v[108:111], v[198:201], v[162:165], v[108:111]
	v_mfma_f32_16x16x32_bf16 v[104:107], v[206:209], v[162:165], v[104:107]
	v_mfma_f32_16x16x32_bf16 v[92:95], v[198:201], v[170:173], v[92:95]
	v_mfma_f32_16x16x32_bf16 v[88:91], v[206:209], v[170:173], v[88:91]
	v_mfma_f32_16x16x32_bf16 v[76:79], v[198:201], v[182:185], v[76:79]
	v_mfma_f32_16x16x32_bf16 v[72:75], v[206:209], v[182:185], v[72:75]
	v_mfma_f32_16x16x32_bf16 v[68:71], v[198:201], v[190:193], v[68:71]
	v_mfma_f32_16x16x32_bf16 v[64:67], v[206:209], v[190:193], v[64:67]
	s_mov_b32 m0, s28
	s_barrier
	ds_read_b128 v[158:161], v141 offset:49152
	ds_read_b128 v[162:165], v141 offset:50176
	ds_read_b128 v[166:169], v141 offset:51200
	ds_read_b128 v[170:173], v141 offset:52224
	ds_read_b128 v[178:181], v141 offset:53248
	ds_read_b128 v[182:185], v141 offset:54272
	ds_read_b128 v[186:189], v141 offset:55296
	global_load_lds_dwordx4 v132, s[100:101]
	s_mov_b32 m0, s29
	ds_read_b128 v[190:193], v141 offset:56320
	global_load_lds_dwordx4 v130, s[100:101]
	s_barrier
	s_waitcnt lgkmcnt(0)
	v_mfma_f32_16x16x32_bf16 v[60:63], v[142:145], v[158:161], v[60:63]
	v_mfma_f32_16x16x32_bf16 v[56:59], v[150:153], v[158:161], v[56:59]
	v_mfma_f32_16x16x32_bf16 v[52:55], v[142:145], v[166:169], v[52:55]
	v_mfma_f32_16x16x32_bf16 v[48:51], v[150:153], v[166:169], v[48:51]
	v_mfma_f32_16x16x32_bf16 v[36:39], v[142:145], v[178:181], v[36:39]
	v_mfma_f32_16x16x32_bf16 v[32:35], v[150:153], v[178:181], v[32:35]
	v_mfma_f32_16x16x32_bf16 v[20:23], v[142:145], v[186:189], v[20:23]
	v_mfma_f32_16x16x32_bf16 v[16:19], v[150:153], v[186:189], v[16:19]
	v_mfma_f32_16x16x32_bf16 v[60:63], v[146:149], v[162:165], v[60:63]
	v_mfma_f32_16x16x32_bf16 v[56:59], v[154:157], v[162:165], v[56:59]
	v_mfma_f32_16x16x32_bf16 v[52:55], v[146:149], v[170:173], v[52:55]
	v_mfma_f32_16x16x32_bf16 v[48:51], v[154:157], v[170:173], v[48:51]
	v_mfma_f32_16x16x32_bf16 v[36:39], v[146:149], v[182:185], v[36:39]
	v_mfma_f32_16x16x32_bf16 v[32:35], v[154:157], v[182:185], v[32:35]
	v_mfma_f32_16x16x32_bf16 v[20:23], v[146:149], v[190:193], v[20:23]
	v_mfma_f32_16x16x32_bf16 v[16:19], v[154:157], v[190:193], v[16:19]
	s_barrier
; __device__ __forceinline__ unsigned cvtpk(float lo, float hi) { const f32x2 v = (f32x2){lo, hi}; const bf16v2 b = __builtin_convertvector(v, bf16v2); return __builtin_bit_cast(unsigned, b); }
; #define PG8_STAGE(bufoff, gbase, voff) do { _Pragma("unroll") for (int _i = 0; _i < 2; ++_i) \
;         __builtin_amdgcn_global_load_lds((const unsigned*)((const char*)(gbase) + (voff)[_i]), (PG8_LAS unsigned*)(lds + (bufoff) + ldsw + _i * 8192), 16, 0, 0); } while (0)
; #define PG8_MMA(ai, bj, At, Bt) do { __builtin_amdgcn_s_setprio(1); _Pragma("unroll") for (int m = 0; m < 4; ++m) _Pragma("unroll") for (int n = 0; n < 2; ++n) _Pragma("unroll") for (int k = 0; k < 2; ++k) \
;         acc[ai][bj][m][n] = __builtin_amdgcn_mfma_f32_16x16x32_bf16(Bt[n][k], At[m][k], acc[ai][bj][m][n], 0, 0, 0); __builtin_amdgcn_s_setprio(0); } while (0)
; #define PG8_WAIT_V(n) asm volatile("s_waitcnt vmcnt(" #n ")" ::: "memory")
; #define PG8_BAR __builtin_amdgcn_s_barrier()
; template <class Epi, class Sched>
; __device__ __forceinline__ void gemm_phase(PG8_LAS unsigned char* lds, const Gemm g, const Sched& S, const Epi& E) {
;     ...
;             PG8_STAGE(PG8_SB(1, 1), b3 + hstep, voffB);
;             PG8_WAIT_V(6); PG8_BAR; PG8_MMA(1, 1, At, B1); PG8_BAR;
;         }
;         if constexpr (!Epi::AFTER_DRAIN) { E(acc, cur, wr, wc, fr, fq); S.done(cur); }
;     __device__ __forceinline__ void operator()(const f32x4 (&acc)[2][2][4][2], const pg8::Unit& u, int wr, int wc, int fr, int fq) const {
;         const int row0 = u.pm * 256 + wr * 64 + fr, col0 = u.pn * 256 + wc * 32 + 8 * fq;
; #pragma unroll
;         for (int ai = 0; ai < 2; ++ai)
; #pragma unroll
;             for (int m = 0; m < 4; ++m) { bf16_t* rowp = O + (size_t)(row0 + ai * 128 + m * 16) * ldc + col0;
; #pragma unroll
;                 for (int bj = 0; bj < 2; ++bj) { const f32x4 v0 = acc[ai][bj][m][0], v1 = acc[ai][bj][m][1];
;                     u32x4 w; w.x = cvtpk(v0[0], v0[1]); w.y = cvtpk(v0[2], v0[3]); w.z = cvtpk(v1[0], v1[1]); w.w = cvtpk(v1[2], v1[3]);
;                     *(u32x4*)(rowp + bj * 128) = w; } }
	s_add_i32 m0, s20, 0x1c000
	s_add_u32 s14, s14, 0x40080
	s_addc_u32 s15, s15, 0
	global_load_lds_dwordx4 v176, s[14:15]
	s_add_i32 m0, s20, 0x1e000
	s_nop 0
	global_load_lds_dwordx4 v128, s[14:15]
	s_waitcnt vmcnt(6)
	s_barrier
	v_mfma_f32_16x16x32_bf16 v[44:47], v[194:197], v[158:161], v[44:47]
	v_mfma_f32_16x16x32_bf16 v[40:43], v[202:205], v[158:161], v[40:43]
	v_mfma_f32_16x16x32_bf16 v[28:31], v[194:197], v[166:169], v[28:31]
	v_mfma_f32_16x16x32_bf16 v[24:27], v[202:205], v[166:169], v[24:27]
	v_mfma_f32_16x16x32_bf16 v[12:15], v[194:197], v[178:181], v[12:15]
	v_mfma_f32_16x16x32_bf16 v[8:11], v[202:205], v[178:181], v[8:11]
	v_mfma_f32_16x16x32_bf16 v[4:7], v[194:197], v[186:189], v[4:7]
	v_mfma_f32_16x16x32_bf16 v[0:3], v[202:205], v[186:189], v[0:3]
	v_mfma_f32_16x16x32_bf16 v[44:47], v[198:201], v[162:165], v[44:47]
	v_mfma_f32_16x16x32_bf16 v[40:43], v[206:209], v[162:165], v[40:43]
	v_mfma_f32_16x16x32_bf16 v[28:31], v[198:201], v[170:173], v[28:31]
	v_mfma_f32_16x16x32_bf16 v[24:27], v[206:209], v[170:173], v[24:27]
	v_mfma_f32_16x16x32_bf16 v[12:15], v[198:201], v[182:185], v[12:15]
	v_mfma_f32_16x16x32_bf16 v[8:11], v[206:209], v[182:185], v[8:11]
	v_mfma_f32_16x16x32_bf16 v[4:7], v[198:201], v[190:193], v[4:7]
	v_mfma_f32_16x16x32_bf16 v[0:3], v[206:209], v[190:193], v[0:3]
	s_add_i32 s45, s45, 2
	s_add_u32 s12, s12, 0x100
	s_addc_u32 s13, s13, 0
	s_add_u32 s43, s43, 0x100
	s_addc_u32 s44, s44, 0
	s_cmp_gt_u32 s45, 13
	s_barrier
	s_cbranch_scc0 .LBB0_137
	v_lshl_add_u32 v142, s0, 8, v138
	v_lshl_or_b32 v144, s34, 8, v140
	v_ashrrev_i32_e32 v143, 31, v142
	v_readlane_b32 s12, v253, 18
	v_ashrrev_i32_e32 v145, 31, v144
	v_lshlrev_b64 v[146:147], 11, v[142:143]
	v_readlane_b32 s13, v253, 19
	v_cvt_pk_bf16_f32 v108, v108, v109
	v_cvt_pk_bf16_f32 v109, v110, v111
	v_cvt_pk_bf16_f32 v110, v104, v105
	v_or_b32_e32 v104, 16, v142
	v_cvt_pk_bf16_f32 v92, v92, v93
	v_cvt_pk_bf16_f32 v93, v94, v95
	v_cvt_pk_bf16_f32 v94, v88, v89
	v_or_b32_e32 v88, 32, v142
	v_cvt_pk_bf16_f32 v76, v76, v77
	v_cvt_pk_bf16_f32 v77, v78, v79
	v_cvt_pk_bf16_f32 v78, v72, v73
	v_or_b32_e32 v72, 48, v142
	v_lshl_add_u64 v[146:147], s[12:13], 0, v[146:147]
	v_lshlrev_b64 v[144:145], 1, v[144:145]
	v_ashrrev_i32_e32 v105, 31, v104
	v_ashrrev_i32_e32 v89, 31, v88
	v_ashrrev_i32_e32 v73, 31, v72
	v_lshl_add_u64 v[146:147], v[146:147], 0, v[144:145]
	v_lshlrev_b64 v[104:105], 11, v[104:105]
	v_lshlrev_b64 v[88:89], 11, v[88:89]
	v_lshlrev_b64 v[72:73], 11, v[72:73]
	v_lshl_add_u64 v[104:105], s[12:13], 0, v[104:105]
	v_lshl_add_u64 v[88:89], s[12:13], 0, v[88:89]
	v_lshl_add_u64 v[72:73], s[12:13], 0, v[72:73]
	s_mov_b64 s[12:13], 0x40000
	v_cvt_pk_bf16_f32 v60, v60, v61
	v_cvt_pk_bf16_f32 v61, v62, v63
	v_cvt_pk_bf16_f32 v62, v56, v57
	v_add_co_u32_e32 v56, vcc, s2, v146
	v_cvt_pk_bf16_f32 v68, v68, v69
	v_cvt_pk_bf16_f32 v69, v70, v71
	v_cvt_pk_bf16_f32 v70, v64, v65
	v_lshl_add_u64 v[64:65], v[146:147], 0, s[12:13]
	v_addc_co_u32_e32 v57, vcc, 0, v147, vcc
	v_cvt_pk_bf16_f32 v44, v44, v45
	v_cvt_pk_bf16_f32 v45, v46, v47
	v_cvt_pk_bf16_f32 v46, v40, v41
	v_cvt_pk_bf16_f32 v47, v42, v43
	s_mov_b32 s0, 0x48000
	global_store_dwordx4 v[64:65], v[44:47], off offset:256
	s_mov_b64 s[12:13], 0x48000
	v_cvt_pk_bf16_f32 v28, v28, v29
	v_add_co_u32_e32 v46, vcc, s0, v146
	v_lshl_add_u64 v[44:45], v[146:147], 0, s[12:13]
	s_nop 0
	v_addc_co_u32_e32 v47, vcc, 0, v147, vcc
	v_cvt_pk_bf16_f32 v29, v30, v31
	v_cvt_pk_bf16_f32 v30, v24, v25
	v_cvt_pk_bf16_f32 v31, v26, v27
	s_mov_b32 s0, 0x50000
	global_store_dwordx4 v[44:45], v[28:31], off offset:256
	s_mov_b64 s[12:13], 0x50000
	v_cvt_pk_bf16_f32 v111, v106, v107
	v_add_co_u32_e32 v30, vcc, s0, v146
	v_lshl_add_u64 v[28:29], v[146:147], 0, s[12:13]
	s_nop 0
	v_addc_co_u32_e32 v31, vcc, 0, v147, vcc
	v_cvt_pk_bf16_f32 v12, v12, v13
	v_cvt_pk_bf16_f32 v13, v14, v15
	v_cvt_pk_bf16_f32 v14, v8, v9
	v_cvt_pk_bf16_f32 v15, v10, v11
	s_mov_b32 s0, 0x58000
	global_store_dwordx4 v[146:147], v[108:111], off offset:256
	v_cvt_pk_bf16_f32 v95, v90, v91
	global_store_dwordx4 v[28:29], v[12:15], off offset:256
	v_lshl_add_u64 v[108:109], v[104:105], 0, v[144:145]
	global_store_dwordx4 v[108:109], v[92:95], off offset:256
	v_add_co_u32_e32 v14, vcc, s0, v146
	s_nop 0
	v_lshl_add_u64 v[92:93], v[88:89], 0, v[144:145]
	v_cvt_pk_bf16_f32 v79, v74, v75
	s_mov_b64 s[12:13], 0x58000
	v_addc_co_u32_e32 v15, vcc, 0, v147, vcc
	v_cvt_pk_bf16_f32 v124, v124, v125
	v_cvt_pk_bf16_f32 v125, v126, v127
	v_cvt_pk_bf16_f32 v126, v120, v121
	v_cvt_pk_bf16_f32 v127, v122, v123
	v_cvt_pk_bf16_f32 v104, v116, v117
	v_cvt_pk_bf16_f32 v105, v118, v119
	v_cvt_pk_bf16_f32 v106, v112, v113
	v_cvt_pk_bf16_f32 v107, v114, v115
	v_cvt_pk_bf16_f32 v88, v100, v101
	v_cvt_pk_bf16_f32 v89, v102, v103
	v_cvt_pk_bf16_f32 v90, v96, v97
	v_cvt_pk_bf16_f32 v91, v98, v99
	global_store_dwordx4 v[92:93], v[76:79], off offset:256
	v_cvt_pk_bf16_f32 v74, v80, v81
	v_cvt_pk_bf16_f32 v75, v82, v83
	v_lshl_add_u64 v[76:77], v[72:73], 0, v[144:145]
	v_cvt_pk_bf16_f32 v72, v84, v85
	v_cvt_pk_bf16_f32 v73, v86, v87
	v_cvt_pk_bf16_f32 v71, v66, v67
	v_cvt_pk_bf16_f32 v63, v58, v59
	v_cvt_pk_bf16_f32 v40, v52, v53
	v_cvt_pk_bf16_f32 v41, v54, v55
	v_cvt_pk_bf16_f32 v42, v48, v49
	v_cvt_pk_bf16_f32 v43, v50, v51
	v_cvt_pk_bf16_f32 v24, v36, v37
	v_cvt_pk_bf16_f32 v25, v38, v39
	v_cvt_pk_bf16_f32 v26, v32, v33
	v_cvt_pk_bf16_f32 v27, v34, v35
	v_lshl_add_u64 v[12:13], v[146:147], 0, s[12:13]
	v_cvt_pk_bf16_f32 v8, v20, v21
	v_cvt_pk_bf16_f32 v9, v22, v23
	v_cvt_pk_bf16_f32 v10, v16, v17
	v_cvt_pk_bf16_f32 v11, v18, v19
	v_cvt_pk_bf16_f32 v4, v4, v5
	v_cvt_pk_bf16_f32 v5, v6, v7
	v_cvt_pk_bf16_f32 v6, v0, v1
	v_cvt_pk_bf16_f32 v7, v2, v3
	s_and_b64 vcc, exec, s[38:39]
	s_mov_b32 s34, s4
	s_mov_b32 s0, s6
	s_mov_b64 s[14:15], s[10:11]
	s_mov_b64 s[12:13], s[8:9]
	global_store_dwordx4 v[146:147], v[124:127], off
	global_store_dwordx4 v[108:109], v[104:107], off
	global_store_dwordx4 v[92:93], v[88:91], off
	global_store_dwordx4 v[76:77], v[72:75], off
	global_store_dwordx4 v[76:77], v[68:71], off offset:256
	global_store_dwordx4 v[56:57], v[60:63], off
	global_store_dwordx4 v[46:47], v[40:43], off
	global_store_dwordx4 v[30:31], v[24:27], off
	global_store_dwordx4 v[14:15], v[8:11], off
	global_store_dwordx4 v[12:13], v[4:7], off offset:256
	s_cbranch_vccz .LBB0_134
	s_waitcnt vmcnt(0)
	v_readlane_b32 s22, v255, 14
	s_cmpk_gt_u32 s19, 0xff
	v_readlane_b32 s23, v255, 15
	s_mov_b64 s[28:29], s[54:55]
	s_cbranch_scc1 .LBB0_141
	s_barrier

; #define PG8_STAGE(bufoff, gbase, voff) do { _Pragma("unroll") for (int _i = 0; _i < 2; ++_i) \
;         __builtin_amdgcn_global_load_lds((const unsigned*)((const char*)(gbase) + (voff)[_i]), (PG8_LAS unsigned*)(lds + (bufoff) + ldsw + _i * 8192), 16, 0, 0); } while (0)
; #define PG8_LDA(dst, b, h) do { _Pragma("unroll") for (int m = 0; m < 4; ++m) _Pragma("unroll") for (int k = 0; k < 2; ++k) dst[m][k] = *(const PG8_LAS bf16x8*)(lds + PG8_SA(b, h) + aoff + m * 2048 + k * 1024); } while (0)
; #define PG8_LDB(dst, b, h) do { _Pragma("unroll") for (int n = 0; n < 2; ++n) _Pragma("unroll") for (int k = 0; k < 2; ++k) dst[n][k] = *(const PG8_LAS bf16x8*)(lds + PG8_SB(b, h) + boff + n * 2048 + k * 1024); } while (0)
; #define PG8_MMA(ai, bj, At, Bt) do { __builtin_amdgcn_s_setprio(1); _Pragma("unroll") for (int m = 0; m < 4; ++m) _Pragma("unroll") for (int n = 0; n < 2; ++n) _Pragma("unroll") for (int k = 0; k < 2; ++k) \
;         acc[ai][bj][m][n] = __builtin_amdgcn_mfma_f32_16x16x32_bf16(Bt[n][k], At[m][k], acc[ai][bj][m][n], 0, 0, 0); __builtin_amdgcn_s_setprio(0); } while (0)
; #define PG8_WAIT_V(n) asm volatile("s_waitcnt vmcnt(" #n ")" ::: "memory")
; #define PG8_WAIT_L(n) asm volatile("s_waitcnt lgkmcnt(" #n ")" ::: "memory")
; #define PG8_BAR __builtin_amdgcn_s_barrier()
; #define PG8_SCHED __builtin_amdgcn_sched_barrier(0)
; template <class Epi, class Sched>
; __device__ __forceinline__ void gemm_phase(PG8_LAS unsigned char* lds, const Gemm g, const Sched& S, const Epi& E) {
;     ...
;             PG8_LDB(B0, 0, 0); PG8_SCHED; PG8_LDA(At, 0, 0); PG8_STAGE(PG8_SA(1, 1), a1 + hstep, voffA);
;             PG8_WAIT_L(8); PG8_BAR; PG8_WAIT_L(0); PG8_MMA(0, 0, At, B0); PG8_BAR; PG8_SCHED;
;             PG8_LDB(B1, 0, 1); PG8_STAGE(PG8_SB(0, 0), b2, voffB);
;             PG8_BAR; PG8_WAIT_L(0); PG8_MMA(0, 1, At, B1); PG8_BAR;
;             PG8_LDA(At, 0, 1); PG8_STAGE(PG8_SA(0, 0), a2, voffA);
;             PG8_BAR; PG8_WAIT_L(0); PG8_MMA(1, 0, At, B0); PG8_BAR; PG8_SCHED;
;             PG8_STAGE(PG8_SB(0, 1), b2 + hstep, voffB);
;             PG8_WAIT_V(6); PG8_BAR; PG8_MMA(1, 1, At, B1); PG8_BAR;
.LBB0_358:
	s_add_u32 s14, s12, 0xfffc0080
	s_addc_u32 s15, s13, -1
	v_add_u32_e32 v154, 0x10000, v139
	ds_read_b128 v[142:145], v154
	ds_read_b128 v[146:149], v154 offset:1024
	ds_read_b128 v[150:153], v154 offset:2048
	ds_read_b128 v[154:157], v154 offset:3072
	s_cmp_eq_u32 s45, 12
	s_cselect_b32 s17, s7, s15
	s_cselect_b32 s16, s40, s14
	s_cselect_b32 s15, s5, s44
	s_cselect_b32 s14, s41, s43
	s_add_i32 m0, s1, 0xc000
	ds_read_b128 v[158:161], v141
	ds_read_b128 v[162:165], v141 offset:1024
	ds_read_b128 v[166:169], v141 offset:2048
	ds_read_b128 v[170:173], v141 offset:3072
	ds_read_b128 v[182:185], v141 offset:4096
	ds_read_b128 v[190:193], v141 offset:5120
	ds_read_b128 v[194:197], v141 offset:6144
	global_load_lds_dwordx4 v134, s[12:13]
	s_add_i32 m0, s1, 0xe000
	ds_read_b128 v[198:201], v141 offset:7168
	global_load_lds_dwordx4 v136, s[12:13]
	s_waitcnt lgkmcnt(8)
	s_barrier
	s_waitcnt lgkmcnt(0)
	v_mfma_f32_16x16x32_bf16 v[124:127], v[142:145], v[158:161], v[124:127]
	v_mfma_f32_16x16x32_bf16 v[120:123], v[150:153], v[158:161], v[120:123]
	v_mfma_f32_16x16x32_bf16 v[116:119], v[142:145], v[166:169], v[116:119]
	v_mfma_f32_16x16x32_bf16 v[112:115], v[150:153], v[166:169], v[112:115]
	v_mfma_f32_16x16x32_bf16 v[100:103], v[142:145], v[182:185], v[100:103]
	v_mfma_f32_16x16x32_bf16 v[96:99], v[150:153], v[182:185], v[96:99]
	v_mfma_f32_16x16x32_bf16 v[84:87], v[142:145], v[194:197], v[84:87]
	v_mfma_f32_16x16x32_bf16 v[80:83], v[150:153], v[194:197], v[80:83]
	v_mfma_f32_16x16x32_bf16 v[124:127], v[146:149], v[162:165], v[124:127]
	v_mfma_f32_16x16x32_bf16 v[120:123], v[154:157], v[162:165], v[120:123]
	v_mfma_f32_16x16x32_bf16 v[116:119], v[146:149], v[170:173], v[116:119]
	v_mfma_f32_16x16x32_bf16 v[112:115], v[154:157], v[170:173], v[112:115]
	v_mfma_f32_16x16x32_bf16 v[100:103], v[146:149], v[190:193], v[100:103]
	v_mfma_f32_16x16x32_bf16 v[96:99], v[154:157], v[190:193], v[96:99]
	v_mfma_f32_16x16x32_bf16 v[84:87], v[146:149], v[198:201], v[84:87]
	v_mfma_f32_16x16x32_bf16 v[80:83], v[154:157], v[198:201], v[80:83]
	s_barrier
	s_add_i32 s48, 0, 0x14000
	v_add_u32_e32 v174, 0x14000, v139
	ds_read_b128 v[202:205], v174
	ds_read_b128 v[206:209], v174 offset:1024
	s_add_u32 s98, s14, 0x80
	s_addc_u32 s99, s15, 0
	s_add_i32 m0, s20, 0x10000
	ds_read_b128 v[210:213], v174 offset:2048
	global_load_lds_dwordx4 v176, s[14:15]
	s_add_i32 m0, s20, 0x12000
	ds_read_b128 v[214:217], v174 offset:3072
	global_load_lds_dwordx4 v128, s[14:15]
	s_barrier
	s_waitcnt lgkmcnt(0)
	v_mfma_f32_16x16x32_bf16 v[108:111], v[202:205], v[158:161], v[108:111]
	v_mfma_f32_16x16x32_bf16 v[104:107], v[210:213], v[158:161], v[104:107]
	v_mfma_f32_16x16x32_bf16 v[92:95], v[202:205], v[166:169], v[92:95]
	v_mfma_f32_16x16x32_bf16 v[88:91], v[210:213], v[166:169], v[88:91]
	v_mfma_f32_16x16x32_bf16 v[76:79], v[202:205], v[182:185], v[76:79]
	v_mfma_f32_16x16x32_bf16 v[72:75], v[210:213], v[182:185], v[72:75]
	v_mfma_f32_16x16x32_bf16 v[68:71], v[202:205], v[194:197], v[68:71]
	v_mfma_f32_16x16x32_bf16 v[64:67], v[210:213], v[194:197], v[64:67]
	v_mfma_f32_16x16x32_bf16 v[108:111], v[206:209], v[162:165], v[108:111]
	v_mfma_f32_16x16x32_bf16 v[104:107], v[214:217], v[162:165], v[104:107]
	v_mfma_f32_16x16x32_bf16 v[92:95], v[206:209], v[170:173], v[92:95]
	v_mfma_f32_16x16x32_bf16 v[88:91], v[214:217], v[170:173], v[88:91]
	v_mfma_f32_16x16x32_bf16 v[76:79], v[206:209], v[190:193], v[76:79]
	v_mfma_f32_16x16x32_bf16 v[72:75], v[214:217], v[190:193], v[72:75]
	v_mfma_f32_16x16x32_bf16 v[68:71], v[206:209], v[198:201], v[68:71]
	v_mfma_f32_16x16x32_bf16 v[64:67], v[214:217], v[198:201], v[64:67]
	s_mov_b32 m0, s1
	s_add_u32 s100, s16, 0x80
	s_addc_u32 s101, s17, 0
	s_barrier
	ds_read_b128 v[158:161], v141 offset:16384
	ds_read_b128 v[162:165], v141 offset:17408
	ds_read_b128 v[166:169], v141 offset:18432
	ds_read_b128 v[170:173], v141 offset:19456
	ds_read_b128 v[182:185], v141 offset:20480
	ds_read_b128 v[190:193], v141 offset:21504
	ds_read_b128 v[194:197], v141 offset:22528
	global_load_lds_dwordx4 v132, s[16:17]
	s_mov_b32 m0, s22
	ds_read_b128 v[198:201], v141 offset:23552
	global_load_lds_dwordx4 v130, s[16:17]
	s_barrier
	s_waitcnt lgkmcnt(0)
	v_mfma_f32_16x16x32_bf16 v[60:63], v[142:145], v[158:161], v[60:63]
	v_mfma_f32_16x16x32_bf16 v[56:59], v[150:153], v[158:161], v[56:59]
	v_mfma_f32_16x16x32_bf16 v[52:55], v[142:145], v[166:169], v[52:55]
	v_mfma_f32_16x16x32_bf16 v[48:51], v[150:153], v[166:169], v[48:51]
	v_mfma_f32_16x16x32_bf16 v[36:39], v[142:145], v[182:185], v[36:39]
	v_mfma_f32_16x16x32_bf16 v[32:35], v[150:153], v[182:185], v[32:35]
	v_mfma_f32_16x16x32_bf16 v[20:23], v[142:145], v[194:197], v[20:23]
	v_mfma_f32_16x16x32_bf16 v[16:19], v[150:153], v[194:197], v[16:19]
	v_mfma_f32_16x16x32_bf16 v[60:63], v[146:149], v[162:165], v[60:63]
	v_mfma_f32_16x16x32_bf16 v[56:59], v[154:157], v[162:165], v[56:59]
	v_mfma_f32_16x16x32_bf16 v[52:55], v[146:149], v[170:173], v[52:55]
	v_mfma_f32_16x16x32_bf16 v[48:51], v[154:157], v[170:173], v[48:51]
	v_mfma_f32_16x16x32_bf16 v[36:39], v[146:149], v[190:193], v[36:39]
	v_mfma_f32_16x16x32_bf16 v[32:35], v[154:157], v[190:193], v[32:35]
	v_mfma_f32_16x16x32_bf16 v[20:23], v[146:149], v[198:201], v[20:23]
	v_mfma_f32_16x16x32_bf16 v[16:19], v[154:157], v[198:201], v[16:19]
	s_barrier
	s_add_i32 m0, s20, 0x14000
	s_add_u32 s46, s14, 0x40000
	s_addc_u32 s47, s15, 0
	global_load_lds_dwordx4 v176, s[46:47]
	s_add_i32 m0, s20, 0x16000
	s_nop 0
	global_load_lds_dwordx4 v128, s[46:47]
	s_waitcnt vmcnt(6)
	s_barrier
; #define PG8_STAGE(bufoff, gbase, voff) do { _Pragma("unroll") for (int _i = 0; _i < 2; ++_i) \
;         __builtin_amdgcn_global_load_lds((const unsigned*)((const char*)(gbase) + (voff)[_i]), (PG8_LAS unsigned*)(lds + (bufoff) + ldsw + _i * 8192), 16, 0, 0); } while (0)
; #define PG8_LDA(dst, b, h) do { _Pragma("unroll") for (int m = 0; m < 4; ++m) _Pragma("unroll") for (int k = 0; k < 2; ++k) dst[m][k] = *(const PG8_LAS bf16x8*)(lds + PG8_SA(b, h) + aoff + m * 2048 + k * 1024); } while (0)
; #define PG8_LDB(dst, b, h) do { _Pragma("unroll") for (int n = 0; n < 2; ++n) _Pragma("unroll") for (int k = 0; k < 2; ++k) dst[n][k] = *(const PG8_LAS bf16x8*)(lds + PG8_SB(b, h) + boff + n * 2048 + k * 1024); } while (0)
; #define PG8_MMA(ai, bj, At, Bt) do { __builtin_amdgcn_s_setprio(1); _Pragma("unroll") for (int m = 0; m < 4; ++m) _Pragma("unroll") for (int n = 0; n < 2; ++n) _Pragma("unroll") for (int k = 0; k < 2; ++k) \
;         acc[ai][bj][m][n] = __builtin_amdgcn_mfma_f32_16x16x32_bf16(Bt[n][k], At[m][k], acc[ai][bj][m][n], 0, 0, 0); __builtin_amdgcn_s_setprio(0); } while (0)
; #define PG8_WAIT_V(n) asm volatile("s_waitcnt vmcnt(" #n ")" ::: "memory")
; #define PG8_WAIT_L(n) asm volatile("s_waitcnt lgkmcnt(" #n ")" ::: "memory")
; #define PG8_BAR __builtin_amdgcn_s_barrier()
; #define PG8_SCHED __builtin_amdgcn_sched_barrier(0)
; template <class Epi, class Sched>
; __device__ __forceinline__ void gemm_phase(PG8_LAS unsigned char* lds, const Gemm g, const Sched& S, const Epi& E) {
;     ...
;             PG8_WAIT_V(6); PG8_BAR; PG8_MMA(1, 1, At, B1); PG8_BAR;
;             PG8_LDB(B0, 1, 0); PG8_SCHED; PG8_LDA(At, 1, 0); PG8_STAGE(PG8_SA(0, 1), a2 + hstep, voffA);
;             PG8_WAIT_L(8); PG8_BAR; PG8_WAIT_L(0); PG8_MMA(0, 0, At, B0); PG8_BAR; PG8_SCHED;
;             PG8_LDB(B1, 1, 1); PG8_STAGE(PG8_SB(1, 0), b3, voffB);
;             PG8_BAR; PG8_WAIT_L(0); PG8_MMA(0, 1, At, B1); PG8_BAR;
;             PG8_LDA(At, 1, 1); PG8_STAGE(PG8_SA(1, 0), a3, voffA);
;             PG8_BAR; PG8_WAIT_L(0); PG8_MMA(1, 0, At, B0); PG8_BAR; PG8_SCHED;
	v_mfma_f32_16x16x32_bf16 v[44:47], v[202:205], v[158:161], v[44:47]
	v_mfma_f32_16x16x32_bf16 v[40:43], v[210:213], v[158:161], v[40:43]
	v_mfma_f32_16x16x32_bf16 v[28:31], v[202:205], v[166:169], v[28:31]
	v_mfma_f32_16x16x32_bf16 v[24:27], v[210:213], v[166:169], v[24:27]
	v_mfma_f32_16x16x32_bf16 v[12:15], v[202:205], v[182:185], v[12:15]
	v_mfma_f32_16x16x32_bf16 v[8:11], v[210:213], v[182:185], v[8:11]
	v_mfma_f32_16x16x32_bf16 v[4:7], v[202:205], v[194:197], v[4:7]
	v_mfma_f32_16x16x32_bf16 v[0:3], v[210:213], v[194:197], v[0:3]
	v_mfma_f32_16x16x32_bf16 v[44:47], v[206:209], v[162:165], v[44:47]
	v_mfma_f32_16x16x32_bf16 v[40:43], v[214:217], v[162:165], v[40:43]
	v_mfma_f32_16x16x32_bf16 v[28:31], v[206:209], v[170:173], v[28:31]
	v_mfma_f32_16x16x32_bf16 v[24:27], v[214:217], v[170:173], v[24:27]
	v_mfma_f32_16x16x32_bf16 v[12:15], v[206:209], v[190:193], v[12:15]
	v_mfma_f32_16x16x32_bf16 v[8:11], v[214:217], v[190:193], v[8:11]
	v_mfma_f32_16x16x32_bf16 v[4:7], v[206:209], v[198:201], v[4:7]
	v_mfma_f32_16x16x32_bf16 v[0:3], v[214:217], v[198:201], v[0:3]
	v_add_u32_e32 v154, 0x18000, v139
	s_barrier
	ds_read_b128 v[142:145], v154
	ds_read_b128 v[146:149], v154 offset:1024
	ds_read_b128 v[150:153], v154 offset:2048
	ds_read_b128 v[154:157], v154 offset:3072
	s_add_u32 s16, s16, 0x40000
	s_addc_u32 s17, s17, 0
	s_mov_b32 m0, s23
	ds_read_b128 v[158:161], v141 offset:32768
	ds_read_b128 v[162:165], v141 offset:33792
	ds_read_b128 v[166:169], v141 offset:34816
	ds_read_b128 v[170:173], v141 offset:35840
	ds_read_b128 v[182:185], v141 offset:36864
	ds_read_b128 v[190:193], v141 offset:37888
	ds_read_b128 v[194:197], v141 offset:38912
	global_load_lds_dwordx4 v132, s[16:17]
	s_mov_b32 m0, s26
	ds_read_b128 v[198:201], v141 offset:39936
	global_load_lds_dwordx4 v130, s[16:17]
	s_waitcnt lgkmcnt(8)
	s_barrier
	s_waitcnt lgkmcnt(0)
	v_mfma_f32_16x16x32_bf16 v[124:127], v[142:145], v[158:161], v[124:127]
	v_mfma_f32_16x16x32_bf16 v[120:123], v[150:153], v[158:161], v[120:123]
	v_mfma_f32_16x16x32_bf16 v[116:119], v[142:145], v[166:169], v[116:119]
	v_mfma_f32_16x16x32_bf16 v[112:115], v[150:153], v[166:169], v[112:115]
	v_mfma_f32_16x16x32_bf16 v[100:103], v[142:145], v[182:185], v[100:103]
	v_mfma_f32_16x16x32_bf16 v[96:99], v[150:153], v[182:185], v[96:99]
	v_mfma_f32_16x16x32_bf16 v[84:87], v[142:145], v[194:197], v[84:87]
	v_mfma_f32_16x16x32_bf16 v[80:83], v[150:153], v[194:197], v[80:83]
	v_mfma_f32_16x16x32_bf16 v[124:127], v[146:149], v[162:165], v[124:127]
	v_mfma_f32_16x16x32_bf16 v[120:123], v[154:157], v[162:165], v[120:123]
	v_mfma_f32_16x16x32_bf16 v[116:119], v[146:149], v[170:173], v[116:119]
	v_mfma_f32_16x16x32_bf16 v[112:115], v[154:157], v[170:173], v[112:115]
	v_mfma_f32_16x16x32_bf16 v[100:103], v[146:149], v[190:193], v[100:103]
	v_mfma_f32_16x16x32_bf16 v[96:99], v[154:157], v[190:193], v[96:99]
	v_mfma_f32_16x16x32_bf16 v[84:87], v[146:149], v[198:201], v[84:87]
	v_mfma_f32_16x16x32_bf16 v[80:83], v[154:157], v[198:201], v[80:83]
	s_barrier
	v_add_u32_e32 v188, 0x1c000, v139
	s_add_i32 m0, s20, 0x18000
	ds_read_b128 v[202:205], v188
	ds_read_b128 v[206:209], v188 offset:1024
	ds_read_b128 v[210:213], v188 offset:2048
	global_load_lds_dwordx4 v176, s[98:99]
	s_add_i32 m0, s20, 0x1a000
	ds_read_b128 v[214:217], v188 offset:3072
	global_load_lds_dwordx4 v128, s[98:99]
	s_barrier
	s_waitcnt lgkmcnt(0)
	v_mfma_f32_16x16x32_bf16 v[108:111], v[202:205], v[158:161], v[108:111]
	v_mfma_f32_16x16x32_bf16 v[104:107], v[210:213], v[158:161], v[104:107]
	v_mfma_f32_16x16x32_bf16 v[92:95], v[202:205], v[166:169], v[92:95]
	v_mfma_f32_16x16x32_bf16 v[88:91], v[210:213], v[166:169], v[88:91]
	v_mfma_f32_16x16x32_bf16 v[76:79], v[202:205], v[182:185], v[76:79]
	v_mfma_f32_16x16x32_bf16 v[72:75], v[210:213], v[182:185], v[72:75]
	v_mfma_f32_16x16x32_bf16 v[68:71], v[202:205], v[194:197], v[68:71]
	v_mfma_f32_16x16x32_bf16 v[64:67], v[210:213], v[194:197], v[64:67]
	v_mfma_f32_16x16x32_bf16 v[108:111], v[206:209], v[162:165], v[108:111]
	v_mfma_f32_16x16x32_bf16 v[104:107], v[214:217], v[162:165], v[104:107]
	v_mfma_f32_16x16x32_bf16 v[92:95], v[206:209], v[170:173], v[92:95]
	v_mfma_f32_16x16x32_bf16 v[88:91], v[214:217], v[170:173], v[88:91]
	v_mfma_f32_16x16x32_bf16 v[76:79], v[206:209], v[190:193], v[76:79]
	v_mfma_f32_16x16x32_bf16 v[72:75], v[214:217], v[190:193], v[72:75]
	v_mfma_f32_16x16x32_bf16 v[68:71], v[206:209], v[198:201], v[68:71]
	v_mfma_f32_16x16x32_bf16 v[64:67], v[214:217], v[198:201], v[64:67]
	s_mov_b32 m0, s28
	s_barrier
	ds_read_b128 v[158:161], v141 offset:49152
	ds_read_b128 v[162:165], v141 offset:50176
	ds_read_b128 v[166:169], v141 offset:51200
	ds_read_b128 v[170:173], v141 offset:52224
	ds_read_b128 v[182:185], v141 offset:53248
	ds_read_b128 v[190:193], v141 offset:54272
	ds_read_b128 v[194:197], v141 offset:55296
	global_load_lds_dwordx4 v132, s[100:101]
	s_mov_b32 m0, s29
	ds_read_b128 v[198:201], v141 offset:56320
	global_load_lds_dwordx4 v130, s[100:101]
	s_barrier
	s_waitcnt lgkmcnt(0)
	v_mfma_f32_16x16x32_bf16 v[60:63], v[142:145], v[158:161], v[60:63]
	v_mfma_f32_16x16x32_bf16 v[56:59], v[150:153], v[158:161], v[56:59]
	v_mfma_f32_16x16x32_bf16 v[52:55], v[142:145], v[166:169], v[52:55]
	v_mfma_f32_16x16x32_bf16 v[48:51], v[150:153], v[166:169], v[48:51]
	v_mfma_f32_16x16x32_bf16 v[36:39], v[142:145], v[182:185], v[36:39]
	v_mfma_f32_16x16x32_bf16 v[32:35], v[150:153], v[182:185], v[32:35]
	v_mfma_f32_16x16x32_bf16 v[20:23], v[142:145], v[194:197], v[20:23]
	v_mfma_f32_16x16x32_bf16 v[16:19], v[150:153], v[194:197], v[16:19]
	v_mfma_f32_16x16x32_bf16 v[60:63], v[146:149], v[162:165], v[60:63]
	v_mfma_f32_16x16x32_bf16 v[56:59], v[154:157], v[162:165], v[56:59]
	v_mfma_f32_16x16x32_bf16 v[52:55], v[146:149], v[170:173], v[52:55]
	v_mfma_f32_16x16x32_bf16 v[48:51], v[154:157], v[170:173], v[48:51]
	v_mfma_f32_16x16x32_bf16 v[36:39], v[146:149], v[190:193], v[36:39]
	v_mfma_f32_16x16x32_bf16 v[32:35], v[154:157], v[190:193], v[32:35]
	v_mfma_f32_16x16x32_bf16 v[20:23], v[146:149], v[198:201], v[20:23]
	v_mfma_f32_16x16x32_bf16 v[16:19], v[154:157], v[198:201], v[16:19]
	s_barrier
; __device__ __forceinline__ unsigned cvtpk(float lo, float hi) { const f32x2 v = (f32x2){lo, hi}; const bf16v2 b = __builtin_convertvector(v, bf16v2); return __builtin_bit_cast(unsigned, b); }
; #define PG8_STAGE(bufoff, gbase, voff) do { _Pragma("unroll") for (int _i = 0; _i < 2; ++_i) \
;         __builtin_amdgcn_global_load_lds((const unsigned*)((const char*)(gbase) + (voff)[_i]), (PG8_LAS unsigned*)(lds + (bufoff) + ldsw + _i * 8192), 16, 0, 0); } while (0)
; #define PG8_MMA(ai, bj, At, Bt) do { __builtin_amdgcn_s_setprio(1); _Pragma("unroll") for (int m = 0; m < 4; ++m) _Pragma("unroll") for (int n = 0; n < 2; ++n) _Pragma("unroll") for (int k = 0; k < 2; ++k) \
;         acc[ai][bj][m][n] = __builtin_amdgcn_mfma_f32_16x16x32_bf16(Bt[n][k], At[m][k], acc[ai][bj][m][n], 0, 0, 0); __builtin_amdgcn_s_setprio(0); } while (0)
; #define PG8_WAIT_V(n) asm volatile("s_waitcnt vmcnt(" #n ")" ::: "memory")
; #define PG8_BAR __builtin_amdgcn_s_barrier()
; template <class Epi, class Sched>
; __device__ __forceinline__ void gemm_phase(PG8_LAS unsigned char* lds, const Gemm g, const Sched& S, const Epi& E) {
;     ...
;             PG8_STAGE(PG8_SB(1, 1), b3 + hstep, voffB);
;             PG8_WAIT_V(6); PG8_BAR; PG8_MMA(1, 1, At, B1); PG8_BAR;
;         }
;         if constexpr (!Epi::AFTER_DRAIN) { E(acc, cur, wr, wc, fr, fq); S.done(cur); }
;     __device__ __forceinline__ void operator()(const f32x4 (&acc)[2][2][4][2], const pg8::Unit& u, int wr, int wc, int fr, int fq) const {
;         const int row0 = u.pm * 256 + wr * 64 + fr, col0 = u.pn * 256 + wc * 32 + 8 * fq;
; #pragma unroll
;         for (int ai = 0; ai < 2; ++ai)
; #pragma unroll
;             for (int m = 0; m < 4; ++m) { bf16_t* rowp = O + (size_t)(row0 + ai * 128 + m * 16) * ldc + col0;
; #pragma unroll
;                 for (int bj = 0; bj < 2; ++bj) { const f32x4 v0 = acc[ai][bj][m][0], v1 = acc[ai][bj][m][1];
;                     u32x4 w; w.x = cvtpk(v0[0], v0[1]); w.y = cvtpk(v0[2], v0[3]); w.z = cvtpk(v1[0], v1[1]); w.w = cvtpk(v1[2], v1[3]);
;                     *(u32x4*)(rowp + bj * 128) = w; } }
	s_add_i32 m0, s20, 0x1c000
	s_add_u32 s14, s14, 0x40080
	s_addc_u32 s15, s15, 0
	global_load_lds_dwordx4 v176, s[14:15]
	s_add_i32 m0, s20, 0x1e000
	s_nop 0
	global_load_lds_dwordx4 v128, s[14:15]
	s_waitcnt vmcnt(6)
	s_barrier
	v_mfma_f32_16x16x32_bf16 v[44:47], v[202:205], v[158:161], v[44:47]
	v_mfma_f32_16x16x32_bf16 v[40:43], v[210:213], v[158:161], v[40:43]
	v_mfma_f32_16x16x32_bf16 v[28:31], v[202:205], v[166:169], v[28:31]
	v_mfma_f32_16x16x32_bf16 v[24:27], v[210:213], v[166:169], v[24:27]
	v_mfma_f32_16x16x32_bf16 v[12:15], v[202:205], v[182:185], v[12:15]
	v_mfma_f32_16x16x32_bf16 v[8:11], v[210:213], v[182:185], v[8:11]
	v_mfma_f32_16x16x32_bf16 v[4:7], v[202:205], v[194:197], v[4:7]
	v_mfma_f32_16x16x32_bf16 v[0:3], v[210:213], v[194:197], v[0:3]
	v_mfma_f32_16x16x32_bf16 v[44:47], v[206:209], v[162:165], v[44:47]
	v_mfma_f32_16x16x32_bf16 v[40:43], v[214:217], v[162:165], v[40:43]
	v_mfma_f32_16x16x32_bf16 v[28:31], v[206:209], v[170:173], v[28:31]
	v_mfma_f32_16x16x32_bf16 v[24:27], v[214:217], v[170:173], v[24:27]
	v_mfma_f32_16x16x32_bf16 v[12:15], v[206:209], v[190:193], v[12:15]
	v_mfma_f32_16x16x32_bf16 v[8:11], v[214:217], v[190:193], v[8:11]
	v_mfma_f32_16x16x32_bf16 v[4:7], v[206:209], v[198:201], v[4:7]
	v_mfma_f32_16x16x32_bf16 v[0:3], v[214:217], v[198:201], v[0:3]
	s_add_i32 s45, s45, 2
	s_add_u32 s12, s12, 0x100
	s_addc_u32 s13, s13, 0
	s_add_u32 s43, s43, 0x100
	s_addc_u32 s44, s44, 0
	s_cmp_gt_u32 s45, 13
	s_barrier
	s_cbranch_scc0 .LBB0_358
	v_readlane_b32 s12, v253, 16
	v_lshl_add_u32 v148, s0, 8, v138
	v_lshl_or_b32 v142, s34, 8, v140
	v_readlane_b32 s13, v253, 17
	v_ashrrev_i32_e32 v143, 31, v142
	v_cvt_pk_bf16_f32 v68, v68, v69
	v_mov_b64_e32 v[144:145], s[12:13]
	v_cvt_pk_bf16_f32 v69, v70, v71
	v_cvt_pk_bf16_f32 v70, v64, v65
	v_add_u32_e32 v64, 0x80, v148
	v_mad_i64_i32 v[146:147], s[12:13], v148, s81, v[144:145]
	v_lshlrev_b64 v[142:143], 1, v[142:143]
	v_cvt_pk_bf16_f32 v108, v108, v109
	v_cvt_pk_bf16_f32 v109, v110, v111
	v_cvt_pk_bf16_f32 v110, v104, v105
	v_or_b32_e32 v104, 16, v148
	v_mad_i64_i32 v[64:65], s[12:13], v64, s81, v[144:145]
	v_cvt_pk_bf16_f32 v44, v44, v45
	v_cvt_pk_bf16_f32 v45, v46, v47
	v_cvt_pk_bf16_f32 v46, v40, v41
	v_add_u32_e32 v40, 0x90, v148
	v_lshl_add_u64 v[146:147], v[146:147], 0, v[142:143]
	v_cvt_pk_bf16_f32 v111, v106, v107
	v_mad_i64_i32 v[104:105], s[12:13], v104, s81, v[144:145]
	v_cvt_pk_bf16_f32 v92, v92, v93
	v_cvt_pk_bf16_f32 v93, v94, v95
	v_cvt_pk_bf16_f32 v94, v88, v89
	v_or_b32_e32 v88, 32, v148
	v_lshl_add_u64 v[64:65], v[64:65], 0, v[142:143]
	v_cvt_pk_bf16_f32 v47, v42, v43
	v_mad_i64_i32 v[40:41], s[12:13], v40, s81, v[144:145]
	v_cvt_pk_bf16_f32 v28, v28, v29
	v_cvt_pk_bf16_f32 v29, v30, v31
	v_cvt_pk_bf16_f32 v30, v24, v25
	v_add_u32_e32 v24, 0xa0, v148
	global_store_dwordx4 v[146:147], v[108:111], off offset:256
	v_cvt_pk_bf16_f32 v95, v90, v91
	v_mad_i64_i32 v[88:89], s[12:13], v88, s81, v[144:145]
	v_lshl_add_u64 v[108:109], v[104:105], 0, v[142:143]
	v_cvt_pk_bf16_f32 v76, v76, v77
	v_cvt_pk_bf16_f32 v77, v78, v79
	v_cvt_pk_bf16_f32 v78, v72, v73
	v_or_b32_e32 v72, 48, v148
	global_store_dwordx4 v[64:65], v[44:47], off offset:256
	v_cvt_pk_bf16_f32 v31, v26, v27
	v_mad_i64_i32 v[24:25], s[12:13], v24, s81, v[144:145]
	v_lshl_add_u64 v[44:45], v[40:41], 0, v[142:143]
	v_cvt_pk_bf16_f32 v12, v12, v13
	v_cvt_pk_bf16_f32 v13, v14, v15
	v_cvt_pk_bf16_f32 v14, v8, v9
	v_add_u32_e32 v8, 0xb0, v148
	global_store_dwordx4 v[108:109], v[92:95], off offset:256
	v_cvt_pk_bf16_f32 v79, v74, v75
	v_mad_i64_i32 v[72:73], s[12:13], v72, s81, v[144:145]
	v_lshl_add_u64 v[92:93], v[88:89], 0, v[142:143]
	global_store_dwordx4 v[44:45], v[28:31], off offset:256
	v_cvt_pk_bf16_f32 v15, v10, v11
	v_mad_i64_i32 v[8:9], s[12:13], v8, s81, v[144:145]
	v_lshl_add_u64 v[28:29], v[24:25], 0, v[142:143]
	v_cvt_pk_bf16_f32 v124, v124, v125
	v_cvt_pk_bf16_f32 v125, v126, v127
	v_cvt_pk_bf16_f32 v126, v120, v121
	v_cvt_pk_bf16_f32 v127, v122, v123
	v_cvt_pk_bf16_f32 v104, v116, v117
	v_cvt_pk_bf16_f32 v105, v118, v119
	v_cvt_pk_bf16_f32 v106, v112, v113
	v_cvt_pk_bf16_f32 v107, v114, v115
	v_cvt_pk_bf16_f32 v88, v100, v101
	v_cvt_pk_bf16_f32 v89, v102, v103
	v_cvt_pk_bf16_f32 v90, v96, v97
	v_cvt_pk_bf16_f32 v91, v98, v99
	global_store_dwordx4 v[92:93], v[76:79], off offset:256
	v_cvt_pk_bf16_f32 v74, v80, v81
	v_cvt_pk_bf16_f32 v75, v82, v83
	v_lshl_add_u64 v[76:77], v[72:73], 0, v[142:143]
	v_cvt_pk_bf16_f32 v72, v84, v85
	v_cvt_pk_bf16_f32 v73, v86, v87
	v_cvt_pk_bf16_f32 v71, v66, v67
	v_cvt_pk_bf16_f32 v60, v60, v61
	v_cvt_pk_bf16_f32 v61, v62, v63
	v_cvt_pk_bf16_f32 v62, v56, v57
	v_cvt_pk_bf16_f32 v63, v58, v59
	v_cvt_pk_bf16_f32 v40, v52, v53
	v_cvt_pk_bf16_f32 v41, v54, v55
	v_cvt_pk_bf16_f32 v42, v48, v49
	v_cvt_pk_bf16_f32 v43, v50, v51
	v_cvt_pk_bf16_f32 v24, v36, v37
	v_cvt_pk_bf16_f32 v25, v38, v39
	v_cvt_pk_bf16_f32 v26, v32, v33
	v_cvt_pk_bf16_f32 v27, v34, v35
	global_store_dwordx4 v[28:29], v[12:15], off offset:256
	v_cvt_pk_bf16_f32 v10, v16, v17
	v_cvt_pk_bf16_f32 v11, v18, v19
	v_lshl_add_u64 v[12:13], v[8:9], 0, v[142:143]
	v_cvt_pk_bf16_f32 v8, v20, v21
	v_cvt_pk_bf16_f32 v9, v22, v23
	v_cvt_pk_bf16_f32 v4, v4, v5
	v_cvt_pk_bf16_f32 v5, v6, v7
	v_cvt_pk_bf16_f32 v6, v0, v1
	v_cvt_pk_bf16_f32 v7, v2, v3
	s_and_b64 vcc, exec, s[38:39]
	s_mov_b32 s34, s4
	s_mov_b32 s0, s6
	s_mov_b64 s[14:15], s[10:11]
	s_mov_b64 s[12:13], s[8:9]
	global_store_dwordx4 v[146:147], v[124:127], off
	global_store_dwordx4 v[108:109], v[104:107], off
	global_store_dwordx4 v[92:93], v[88:91], off
	global_store_dwordx4 v[76:77], v[72:75], off
	global_store_dwordx4 v[76:77], v[68:71], off offset:256
	global_store_dwordx4 v[64:65], v[60:63], off
	global_store_dwordx4 v[44:45], v[40:43], off
	global_store_dwordx4 v[28:29], v[24:27], off
	global_store_dwordx4 v[12:13], v[8:11], off
	global_store_dwordx4 v[12:13], v[4:7], off offset:256
	s_cbranch_vccz .LBB0_355
	s_waitcnt vmcnt(0)
	v_readlane_b32 s22, v255, 14
	s_cmpk_gt_u32 s19, 0xff
	v_readlane_b32 s23, v255, 15
	s_mov_b64 s[28:29], s[54:55]
	s_cbranch_scc1 .LBB0_362
	s_barrier
